# ph0: nt policy also on the bf16 weight stores of the transpose items; on top of v47
# speedup vs baseline: 1.0019x; 1.0019x over previous
.LBB0_35:
	s_lshl_b32 s7, s4, 1
	s_lshl_b32 s6, s3, 1
	v_or_b32_e32 v75, s7, v54
	s_add_i32 s27, s7, 4
	v_or_b32_e32 v73, s6, v17
	s_add_i32 s26, s6, 4
	s_add_i32 s72, s7, 8
	v_add_lshl_u32 v18, v75, s1, 11
	v_or_b32_e32 v79, s27, v54
	v_mov_b32_e32 v3, v19
	s_add_i32 s74, s7, 12
	v_add_lshl_u32 v2, v73, s2, 11
	v_or_b32_e32 v77, s26, v17
	v_or_b32_e32 v114, s72, v54
	v_lshl_add_u64 v[90:91], v[18:19], 2, v[0:1]
	v_add_lshl_u32 v18, v79, s1, 11
	v_mov_b32_e32 v5, v19
	s_add_i32 s71, s6, 8
	s_add_i32 s73, s6, 12
	s_add_i32 s76, s7, 16
	v_or_b32_e32 v116, s74, v54
	v_lshl_add_u64 v[2:3], v[2:3], 2, v[0:1]
	v_add_lshl_u32 v4, v77, s2, 11
	v_lshl_add_u64 v[112:113], v[18:19], 2, v[0:1]
	v_add_lshl_u32 v18, v114, s1, 11
	s_add_i32 s78, s7, 20
	v_or_b32_e32 v111, s71, v17
	v_or_b32_e32 v115, s73, v17
	v_or_b32_e32 v118, s76, v54
	v_lshl_add_u64 v[4:5], v[4:5], 2, v[0:1]
	global_load_dword v126, v[90:91], off nt
	global_load_dword v127, v[2:3], off nt
	global_load_dword v128, v[112:113], off nt
	global_load_dword v129, v[4:5], off nt
	v_lshl_add_u64 v[2:3], v[18:19], 2, v[0:1]
	v_add_lshl_u32 v18, v116, s1, 11
	v_mov_b32_e32 v7, v19
	v_mov_b32_e32 v9, v19
	s_add_i32 s75, s6, 16
	s_add_i32 s77, s6, 20
	s_add_i32 s80, s7, 24
	v_or_b32_e32 v120, s78, v54
	v_add_lshl_u32 v6, v111, s2, 11
	v_add_lshl_u32 v8, v115, s2, 11
	v_lshl_add_u64 v[4:5], v[18:19], 2, v[0:1]
	v_add_lshl_u32 v18, v118, s1, 11
	s_add_i32 s79, s6, 24
	s_add_i32 s6, s6, 28
	s_add_i32 s7, s7, 28
	v_or_b32_e32 v117, s75, v17
	v_or_b32_e32 v119, s77, v17
	v_or_b32_e32 v122, s80, v54
	v_lshl_add_u64 v[6:7], v[6:7], 2, v[0:1]
	v_lshl_add_u64 v[8:9], v[8:9], 2, v[0:1]
	global_load_dword v130, v[2:3], off nt
	global_load_dword v131, v[6:7], off nt
	global_load_dword v132, v[4:5], off nt
	global_load_dword v133, v[8:9], off nt
	v_lshl_add_u64 v[2:3], v[18:19], 2, v[0:1]
	v_add_lshl_u32 v18, v120, s1, 11
	v_mov_b32_e32 v11, v19
	v_mov_b32_e32 v13, v19
	v_or_b32_e32 v121, s79, v17
	v_or_b32_e32 v124, s6, v17
	v_or_b32_e32 v123, s7, v54
	v_add_lshl_u32 v10, v117, s2, 11
	v_add_lshl_u32 v12, v119, s2, 11
	v_lshl_add_u64 v[4:5], v[18:19], 2, v[0:1]
	v_add_lshl_u32 v18, v122, s1, 11
	v_mov_b32_e32 v15, v19
	v_mov_b32_e32 v89, v19
	v_add_lshl_u32 v14, v121, s2, 11
	v_add_lshl_u32 v88, v124, s2, 11
	v_lshl_add_u64 v[10:11], v[10:11], 2, v[0:1]
	v_lshl_add_u64 v[12:13], v[12:13], 2, v[0:1]
	global_load_dword v134, v[2:3], off nt
	global_load_dword v135, v[10:11], off nt
	global_load_dword v136, v[4:5], off nt
	global_load_dword v137, v[12:13], off nt
	v_lshl_add_u64 v[2:3], v[18:19], 2, v[0:1]
	v_add_lshl_u32 v18, v123, s1, 11
	v_lshl_add_u64 v[14:15], v[14:15], 2, v[0:1]
	v_lshl_add_u64 v[88:89], v[88:89], 2, v[0:1]
	v_lshl_add_u64 v[4:5], v[18:19], 2, v[0:1]
	global_load_dword v18, v[2:3], off nt
	global_load_dword v138, v[14:15], off nt
	global_load_dword v139, v[4:5], off nt
	global_load_dword v140, v[88:89], off nt
	s_add_i32 s4, s4, 16
	s_add_i32 s3, s3, 16
	s_add_i32 s5, s5, -16
	v_mad_u64_u32 v[2:3], s[6:7], v75, s49, v[56:57]
	s_cmp_lg_u32 s5, 0
	v_mad_u64_u32 v[4:5], s[6:7], v73, s49, v[56:57]
	v_mad_u64_u32 v[6:7], s[6:7], v79, s49, v[56:57]
	v_mad_u64_u32 v[8:9], s[6:7], v77, s49, v[56:57]
	v_mad_u64_u32 v[10:11], s[6:7], v114, s49, v[56:57]
	v_mad_u64_u32 v[12:13], s[6:7], v111, s49, v[56:57]
	v_mad_u64_u32 v[14:15], s[6:7], v116, s49, v[56:57]
	v_mad_u64_u32 v[88:89], s[6:7], v115, s49, v[56:57]
	v_mad_u64_u32 v[90:91], s[6:7], v118, s49, v[56:57]
	v_mad_u64_u32 v[112:113], s[6:7], v117, s49, v[56:57]
	v_mad_u64_u32 v[114:115], s[6:7], v120, s49, v[56:57]
	v_mad_u64_u32 v[116:117], s[6:7], v119, s49, v[56:57]
	v_mad_u64_u32 v[118:119], s[6:7], v122, s49, v[56:57]
	v_mad_u64_u32 v[120:121], s[6:7], v121, s49, v[56:57]
	v_mad_u64_u32 v[122:123], s[6:7], v123, s49, v[56:57]
	v_mad_u64_u32 v[124:125], s[6:7], v124, s49, v[56:57]
	s_waitcnt vmcnt(0)
	ds_write_b32 v2, v126
	ds_write_b32 v4, v127
	ds_write_b32 v6, v128
	ds_write_b32 v8, v129
	ds_write_b32 v10, v130
	ds_write_b32 v12, v131
	ds_write_b32 v14, v132
	ds_write_b32 v88, v133
	ds_write_b32 v90, v134
	ds_write_b32 v112, v135
	ds_write_b32 v114, v136
	ds_write_b32 v116, v137
	ds_write_b32 v118, v18
	ds_write_b32 v120, v138
	ds_write_b32 v122, v139
	ds_write_b32 v124, v140
	s_cbranch_scc1 .LBB0_35
	s_waitcnt lgkmcnt(0)
	ds_read2_b32 v[4:5], v94 offset1:8
	ds_read2_b32 v[8:9], v94 offset0:33 offset1:41
	ds_read2_b32 v[10:11], v94 offset0:66 offset1:74
	ds_read2_b32 v[12:13], v94 offset0:99 offset1:107
	ds_read2_b32 v[14:15], v94 offset0:132 offset1:140
	s_waitcnt lgkmcnt(0)
	v_bfe_u32 v0, v4, 16, 1
	v_add3_u32 v0, v4, v0, s65
	v_bfe_u32 v1, v8, 16, 1
	v_lshrrev_b32_e32 v0, 16, v0
	v_add3_u32 v1, v8, v1, s65
	ds_read2_b32 v[88:89], v94 offset0:165 offset1:173
	v_and_or_b32 v0, v1, s66, v0
	v_bfe_u32 v1, v10, 16, 1
	v_add3_u32 v1, v10, v1, s65
	v_bfe_u32 v2, v12, 16, 1
	ds_read2_b32 v[90:91], v94 offset0:198 offset1:206
	v_lshrrev_b32_e32 v1, 16, v1
	v_add3_u32 v2, v12, v2, s65
	ds_read2_b32 v[112:113], v94 offset0:231 offset1:239
	v_and_or_b32 v1, v2, s66, v1
	v_bfe_u32 v2, v14, 16, 1
	v_add3_u32 v2, v14, v2, s65
	s_waitcnt lgkmcnt(2)
	v_bfe_u32 v3, v88, 16, 1
	s_lshl_b64 s[2:3], s[24:25], 23
	v_lshrrev_b32_e32 v2, 16, v2
	v_add3_u32 v3, v88, v3, s65
	s_add_u32 s2, s36, s2
	v_and_or_b32 v2, v3, s66, v2
	s_waitcnt lgkmcnt(1)
	v_bfe_u32 v3, v90, 16, 1
	s_addc_u32 s3, s37, s3
	s_lshl_b32 s1, s1, 1
	v_add3_u32 v3, v90, v3, s65
	s_waitcnt lgkmcnt(0)
	v_bfe_u32 v4, v112, 16, 1
	s_add_u32 s2, s2, s1
	v_lshrrev_b32_e32 v3, 16, v3
	v_add3_u32 v4, v112, v4, s65
	s_addc_u32 s3, s3, 0
	v_lshlrev_b32_e32 v18, 1, v24
	v_and_or_b32 v3, v4, s66, v3
	v_or_b32_e32 v4, s0, v25
	v_lshl_add_u64 v[6:7], s[2:3], 0, v[18:19]
	v_lshlrev_b32_e32 v18, 12, v4
	v_lshl_add_u64 v[114:115], v[6:7], 0, v[18:19]
	global_store_dwordx4 v[114:115], v[0:3], off nt
	v_bfe_u32 v4, v113, 16, 1
	v_or_b32_e32 v8, s0, v33
	v_bfe_u32 v0, v5, 16, 1
	v_add3_u32 v0, v5, v0, s65
	v_bfe_u32 v1, v9, 16, 1
	v_lshrrev_b32_e32 v0, 16, v0
	v_add3_u32 v1, v9, v1, s65
	v_and_or_b32 v0, v1, s66, v0
	v_bfe_u32 v1, v11, 16, 1
	v_add3_u32 v1, v11, v1, s65
	v_bfe_u32 v2, v13, 16, 1
	v_lshrrev_b32_e32 v1, 16, v1
	v_add3_u32 v2, v13, v2, s65
	v_and_or_b32 v1, v2, s66, v1
	v_bfe_u32 v2, v15, 16, 1
	v_add3_u32 v2, v15, v2, s65
	v_bfe_u32 v3, v89, 16, 1
	v_lshrrev_b32_e32 v2, 16, v2
	v_add3_u32 v3, v89, v3, s65
	v_and_or_b32 v2, v3, s66, v2
	v_bfe_u32 v3, v91, 16, 1
	v_add3_u32 v3, v91, v3, s65
	v_lshrrev_b32_e32 v3, 16, v3
	v_add3_u32 v4, v113, v4, s65
	v_lshlrev_b32_e32 v18, 12, v8
	v_and_or_b32 v3, v4, s66, v3
	ds_read2_b32 v[4:5], v94 offset0:16 offset1:24
	v_lshl_add_u64 v[8:9], v[6:7], 0, v[18:19]
	global_store_dwordx4 v[8:9], v[0:3], off nt
	ds_read2_b32 v[8:9], v94 offset0:49 offset1:57
	ds_read2_b32 v[10:11], v94 offset0:82 offset1:90
	ds_read2_b32 v[12:13], v94 offset0:115 offset1:123
	s_waitcnt lgkmcnt(3)
	v_bfe_u32 v0, v4, 16, 1
	v_add3_u32 v0, v4, v0, s65
	s_waitcnt lgkmcnt(2)
	v_bfe_u32 v1, v8, 16, 1
	ds_read2_b32 v[14:15], v94 offset0:148 offset1:156
	v_lshrrev_b32_e32 v0, 16, v0
	v_add3_u32 v1, v8, v1, s65
	ds_read2_b32 v[88:89], v94 offset0:181 offset1:189
	v_and_or_b32 v0, v1, s66, v0
	s_waitcnt lgkmcnt(3)
	v_bfe_u32 v1, v10, 16, 1
	v_add3_u32 v1, v10, v1, s65
	s_waitcnt lgkmcnt(2)
	v_bfe_u32 v2, v12, 16, 1
	ds_read2_b32 v[90:91], v94 offset0:214 offset1:222
	v_lshrrev_b32_e32 v1, 16, v1
	v_add3_u32 v2, v12, v2, s65
	ds_read2_b32 v[112:113], v94 offset0:247 offset1:255
	v_and_or_b32 v1, v2, s66, v1
	s_waitcnt lgkmcnt(3)
	v_bfe_u32 v2, v14, 16, 1
	v_add3_u32 v2, v14, v2, s65
	s_waitcnt lgkmcnt(2)
	v_bfe_u32 v3, v88, 16, 1
	v_lshrrev_b32_e32 v2, 16, v2
	v_add3_u32 v3, v88, v3, s65
	v_and_or_b32 v2, v3, s66, v2
	s_waitcnt lgkmcnt(1)
	v_bfe_u32 v3, v90, 16, 1
	v_add3_u32 v3, v90, v3, s65
	s_waitcnt lgkmcnt(0)
	v_bfe_u32 v4, v112, 16, 1
	v_lshrrev_b32_e32 v3, 16, v3
	v_add3_u32 v4, v112, v4, s65
	v_and_or_b32 v3, v4, s66, v3
	v_or_b32_e32 v4, s0, v55
	v_lshlrev_b32_e32 v18, 12, v4
	v_lshl_add_u64 v[114:115], v[6:7], 0, v[18:19]
	global_store_dwordx4 v[114:115], v[0:3], off nt
	v_bfe_u32 v4, v113, 16, 1
	v_add3_u32 v4, v113, v4, s65
	v_bfe_u32 v0, v5, 16, 1
	v_add3_u32 v0, v5, v0, s65
	v_bfe_u32 v1, v9, 16, 1
	v_lshrrev_b32_e32 v0, 16, v0
	v_add3_u32 v1, v9, v1, s65
	v_and_or_b32 v0, v1, s66, v0
	v_bfe_u32 v1, v11, 16, 1
	v_add3_u32 v1, v11, v1, s65
	v_bfe_u32 v2, v13, 16, 1
	v_lshrrev_b32_e32 v1, 16, v1
	v_add3_u32 v2, v13, v2, s65
	v_and_or_b32 v1, v2, s66, v1
	v_bfe_u32 v2, v15, 16, 1
	v_add3_u32 v2, v15, v2, s65
	v_bfe_u32 v3, v89, 16, 1
	v_lshrrev_b32_e32 v2, 16, v2
	v_add3_u32 v3, v89, v3, s65
	v_and_or_b32 v2, v3, s66, v2
	v_bfe_u32 v3, v91, 16, 1
	v_add3_u32 v3, v91, v3, s65
	v_lshrrev_b32_e32 v3, 16, v3
	v_and_or_b32 v3, v4, s66, v3
	v_or_b32_e32 v4, s0, v57
	v_lshlrev_b32_e32 v18, 12, v4
	v_lshl_add_u64 v[4:5], v[6:7], 0, v[18:19]
	global_store_dwordx4 v[4:5], v[0:3], off nt
	s_waitcnt lgkmcnt(0)

.LBB0_61:
	s_waitcnt lgkmcnt(0)
	ds_read2_b32 v[4:5], v94 offset1:8
	ds_read2_b32 v[8:9], v94 offset0:33 offset1:41
	ds_read2_b32 v[10:11], v94 offset0:66 offset1:74
	ds_read2_b32 v[12:13], v94 offset0:99 offset1:107
	ds_read2_b32 v[14:15], v94 offset0:132 offset1:140
	s_waitcnt lgkmcnt(0)
	v_bfe_u32 v0, v4, 16, 1
	v_add3_u32 v0, v4, v0, s65
	v_bfe_u32 v1, v8, 16, 1
	v_lshrrev_b32_e32 v0, 16, v0
	v_add3_u32 v1, v8, v1, s65
	ds_read2_b32 v[88:89], v94 offset0:165 offset1:173
	v_and_or_b32 v0, v1, s66, v0
	v_bfe_u32 v1, v10, 16, 1
	s_and_b64 s[0:1], s[2:3], exec
	v_add3_u32 v1, v10, v1, s65
	v_bfe_u32 v2, v12, 16, 1
	ds_read2_b32 v[90:91], v94 offset0:198 offset1:206
	s_mov_b32 s0, 0x11d00000
	v_lshrrev_b32_e32 v1, 16, v1
	v_add3_u32 v2, v12, v2, s65
	ds_read2_b32 v[112:113], v94 offset0:231 offset1:239
	s_cselect_b32 s0, s0, 0x12400000
	v_and_or_b32 v1, v2, s66, v1
	v_bfe_u32 v2, v14, 16, 1
	s_cselect_b32 s1, 0x1000, 0
	s_add_u32 s0, s28, s0
	v_add3_u32 v2, v14, v2, s65
	s_waitcnt lgkmcnt(2)
	v_bfe_u32 v3, v88, 16, 1
	s_addc_u32 s2, s29, 0
	s_add_i32 s3, s6, s1
	s_lshl_b32 s1, s7, 1
	v_lshrrev_b32_e32 v2, 16, v2
	v_add3_u32 v3, v88, v3, s65
	s_add_u32 s0, s0, s1
	v_and_or_b32 v2, v3, s66, v2
	s_waitcnt lgkmcnt(1)
	v_bfe_u32 v3, v90, 16, 1
	s_addc_u32 s1, s2, 0
	v_lshlrev_b32_e32 v18, 1, v24
	v_add3_u32 v3, v90, v3, s65
	s_waitcnt lgkmcnt(0)
	v_bfe_u32 v4, v112, 16, 1
	v_lshl_add_u64 v[6:7], s[0:1], 0, v[18:19]
	v_lshrrev_b32_e32 v3, 16, v3
	v_add3_u32 v4, v112, v4, s65
	v_add_lshl_u32 v18, s3, v25, 10
	v_and_or_b32 v3, v4, s66, v3
	v_lshl_add_u64 v[114:115], v[6:7], 0, v[18:19]
	global_store_dwordx4 v[114:115], v[0:3], off nt
	v_bfe_u32 v4, v113, 16, 1
	v_add3_u32 v4, v113, v4, s65
	v_bfe_u32 v0, v5, 16, 1
	v_add3_u32 v0, v5, v0, s65
	v_bfe_u32 v1, v9, 16, 1
	v_lshrrev_b32_e32 v0, 16, v0
	v_add3_u32 v1, v9, v1, s65
	v_and_or_b32 v0, v1, s66, v0
	v_bfe_u32 v1, v11, 16, 1
	v_add3_u32 v1, v11, v1, s65
	v_bfe_u32 v2, v13, 16, 1
	v_lshrrev_b32_e32 v1, 16, v1
	v_add3_u32 v2, v13, v2, s65
	v_and_or_b32 v1, v2, s66, v1
	v_bfe_u32 v2, v15, 16, 1
	v_add3_u32 v2, v15, v2, s65
	v_bfe_u32 v3, v89, 16, 1
	v_lshrrev_b32_e32 v2, 16, v2
	v_add3_u32 v3, v89, v3, s65
	v_and_or_b32 v2, v3, s66, v2
	v_bfe_u32 v3, v91, 16, 1
	v_add3_u32 v3, v91, v3, s65
	v_lshrrev_b32_e32 v3, 16, v3
	v_add_lshl_u32 v18, s3, v33, 10
	v_and_or_b32 v3, v4, s66, v3
	ds_read2_b32 v[4:5], v94 offset0:16 offset1:24
	v_lshl_add_u64 v[8:9], v[6:7], 0, v[18:19]
	global_store_dwordx4 v[8:9], v[0:3], off nt
	ds_read2_b32 v[8:9], v94 offset0:49 offset1:57
	ds_read2_b32 v[10:11], v94 offset0:82 offset1:90
	ds_read2_b32 v[12:13], v94 offset0:115 offset1:123
	s_waitcnt lgkmcnt(3)
	v_bfe_u32 v0, v4, 16, 1
	v_add3_u32 v0, v4, v0, s65
	s_waitcnt lgkmcnt(2)
	v_bfe_u32 v1, v8, 16, 1
	ds_read2_b32 v[14:15], v94 offset0:148 offset1:156
	v_lshrrev_b32_e32 v0, 16, v0
	v_add3_u32 v1, v8, v1, s65
	ds_read2_b32 v[88:89], v94 offset0:181 offset1:189
	v_and_or_b32 v0, v1, s66, v0
	s_waitcnt lgkmcnt(3)
	v_bfe_u32 v1, v10, 16, 1
	v_add3_u32 v1, v10, v1, s65
	s_waitcnt lgkmcnt(2)
	v_bfe_u32 v2, v12, 16, 1
	ds_read2_b32 v[90:91], v94 offset0:214 offset1:222
	v_lshrrev_b32_e32 v1, 16, v1
	v_add3_u32 v2, v12, v2, s65
	ds_read2_b32 v[112:113], v94 offset0:247 offset1:255
	v_and_or_b32 v1, v2, s66, v1
	s_waitcnt lgkmcnt(3)
	v_bfe_u32 v2, v14, 16, 1
	v_add3_u32 v2, v14, v2, s65
	s_waitcnt lgkmcnt(2)
	v_bfe_u32 v3, v88, 16, 1
	v_lshrrev_b32_e32 v2, 16, v2
	v_add3_u32 v3, v88, v3, s65
	v_and_or_b32 v2, v3, s66, v2
	s_waitcnt lgkmcnt(1)
	v_bfe_u32 v3, v90, 16, 1
	v_add3_u32 v3, v90, v3, s65
	s_waitcnt lgkmcnt(0)
	v_bfe_u32 v4, v112, 16, 1
	v_lshrrev_b32_e32 v3, 16, v3
	v_add3_u32 v4, v112, v4, s65
	v_add_lshl_u32 v18, s3, v55, 10
	v_and_or_b32 v3, v4, s66, v3
	v_lshl_add_u64 v[114:115], v[6:7], 0, v[18:19]
	global_store_dwordx4 v[114:115], v[0:3], off nt
	v_bfe_u32 v4, v113, 16, 1
	v_add3_u32 v4, v113, v4, s65
	v_bfe_u32 v0, v5, 16, 1
	v_add3_u32 v0, v5, v0, s65
	v_bfe_u32 v1, v9, 16, 1
	v_lshrrev_b32_e32 v0, 16, v0
	v_add3_u32 v1, v9, v1, s65
	v_and_or_b32 v0, v1, s66, v0
	v_bfe_u32 v1, v11, 16, 1
	v_add3_u32 v1, v11, v1, s65
	v_bfe_u32 v2, v13, 16, 1
	v_lshrrev_b32_e32 v1, 16, v1
	v_add3_u32 v2, v13, v2, s65
	v_and_or_b32 v1, v2, s66, v1
	v_bfe_u32 v2, v15, 16, 1
	v_add3_u32 v2, v15, v2, s65
	v_bfe_u32 v3, v89, 16, 1
	v_lshrrev_b32_e32 v2, 16, v2
	v_add3_u32 v3, v89, v3, s65
	v_and_or_b32 v2, v3, s66, v2
	v_bfe_u32 v3, v91, 16, 1
	v_add3_u32 v3, v91, v3, s65
	v_lshrrev_b32_e32 v3, 16, v3
	v_add_lshl_u32 v18, s3, v57, 10
	v_and_or_b32 v3, v4, s66, v3
	v_lshl_add_u64 v[4:5], v[6:7], 0, v[18:19]
	global_store_dwordx4 v[4:5], v[0:3], off nt
	s_waitcnt lgkmcnt(0)

.LBB0_82:
	s_waitcnt lgkmcnt(0)
	ds_read2_b32 v[4:5], v94 offset1:8
	ds_read2_b32 v[8:9], v94 offset0:33 offset1:41
	ds_read2_b32 v[10:11], v94 offset0:66 offset1:74
	ds_read2_b32 v[12:13], v94 offset0:99 offset1:107
	ds_read2_b32 v[14:15], v94 offset0:132 offset1:140
	s_waitcnt lgkmcnt(0)
	v_bfe_u32 v0, v4, 16, 1
	v_add3_u32 v0, v4, v0, s65
	v_bfe_u32 v1, v8, 16, 1
	v_lshrrev_b32_e32 v0, 16, v0
	v_add3_u32 v1, v8, v1, s65
	ds_read2_b32 v[88:89], v94 offset0:165 offset1:173
	v_and_or_b32 v0, v1, s66, v0
	v_bfe_u32 v1, v10, 16, 1
	v_add3_u32 v1, v10, v1, s65
	v_bfe_u32 v2, v12, 16, 1
	ds_read2_b32 v[90:91], v94 offset0:198 offset1:206
	v_lshrrev_b32_e32 v1, 16, v1
	v_add3_u32 v2, v12, v2, s65
	ds_read2_b32 v[112:113], v94 offset0:231 offset1:239
	v_and_or_b32 v1, v2, s66, v1
	v_bfe_u32 v2, v14, 16, 1
	v_add3_u32 v2, v14, v2, s65
	s_waitcnt lgkmcnt(2)
	v_bfe_u32 v3, v88, 16, 1
	v_lshrrev_b32_e32 v2, 16, v2
	v_add3_u32 v3, v88, v3, s65
	s_lshl_b32 s1, s70, 5
	s_lshl_b32 s2, s22, 2
	v_and_or_b32 v2, v3, s66, v2
	s_waitcnt lgkmcnt(1)
	v_bfe_u32 v3, v90, 16, 1
	s_and_b32 s1, s1, 0x7e0
	s_and_b32 s2, s2, 0x7ffff800
	v_add3_u32 v3, v90, v3, s65
	s_waitcnt lgkmcnt(0)
	v_bfe_u32 v4, v112, 16, 1
	s_and_b32 s0, s22, 0x1c0
	s_or_b32 s1, s2, s1
	v_lshrrev_b32_e32 v3, 16, v3
	v_add3_u32 v4, v112, v4, s65
	s_lshl_b32 s24, s0, 1
	v_and_or_b32 v3, v4, s66, v3
	v_or_b32_e32 v4, s1, v25
	v_lshl_add_u64 v[6:7], v[26:27], 0, s[24:25]
	v_lshlrev_b32_e32 v18, 10, v4
	v_lshl_add_u64 v[114:115], v[6:7], 0, v[18:19]
	global_store_dwordx4 v[114:115], v[0:3], off nt
	v_bfe_u32 v4, v113, 16, 1
	v_or_b32_e32 v8, s1, v33
	v_bfe_u32 v0, v5, 16, 1
	v_add3_u32 v0, v5, v0, s65
	v_bfe_u32 v1, v9, 16, 1
	v_lshrrev_b32_e32 v0, 16, v0
	v_add3_u32 v1, v9, v1, s65
	v_and_or_b32 v0, v1, s66, v0
	v_bfe_u32 v1, v11, 16, 1
	v_add3_u32 v1, v11, v1, s65
	v_bfe_u32 v2, v13, 16, 1
	v_lshrrev_b32_e32 v1, 16, v1
	v_add3_u32 v2, v13, v2, s65
	v_and_or_b32 v1, v2, s66, v1
	v_bfe_u32 v2, v15, 16, 1
	v_add3_u32 v2, v15, v2, s65
	v_bfe_u32 v3, v89, 16, 1
	v_lshrrev_b32_e32 v2, 16, v2
	v_add3_u32 v3, v89, v3, s65
	v_and_or_b32 v2, v3, s66, v2
	v_bfe_u32 v3, v91, 16, 1
	v_add3_u32 v3, v91, v3, s65
	v_lshrrev_b32_e32 v3, 16, v3
	v_add3_u32 v4, v113, v4, s65
	v_lshlrev_b32_e32 v18, 10, v8
	v_and_or_b32 v3, v4, s66, v3
	ds_read2_b32 v[4:5], v94 offset0:16 offset1:24
	v_lshl_add_u64 v[8:9], v[6:7], 0, v[18:19]
	global_store_dwordx4 v[8:9], v[0:3], off nt
	ds_read2_b32 v[8:9], v94 offset0:49 offset1:57
	ds_read2_b32 v[10:11], v94 offset0:82 offset1:90
	ds_read2_b32 v[12:13], v94 offset0:115 offset1:123
	s_waitcnt lgkmcnt(3)
	v_bfe_u32 v0, v4, 16, 1
	v_add3_u32 v0, v4, v0, s65
	s_waitcnt lgkmcnt(2)
	v_bfe_u32 v1, v8, 16, 1
	ds_read2_b32 v[14:15], v94 offset0:148 offset1:156
	v_lshrrev_b32_e32 v0, 16, v0
	v_add3_u32 v1, v8, v1, s65
	ds_read2_b32 v[88:89], v94 offset0:181 offset1:189
	v_and_or_b32 v0, v1, s66, v0
	s_waitcnt lgkmcnt(3)
	v_bfe_u32 v1, v10, 16, 1
	v_add3_u32 v1, v10, v1, s65
	s_waitcnt lgkmcnt(2)
	v_bfe_u32 v2, v12, 16, 1
	ds_read2_b32 v[90:91], v94 offset0:214 offset1:222
	v_lshrrev_b32_e32 v1, 16, v1
	v_add3_u32 v2, v12, v2, s65
	ds_read2_b32 v[112:113], v94 offset0:247 offset1:255
	v_and_or_b32 v1, v2, s66, v1
	s_waitcnt lgkmcnt(3)
	v_bfe_u32 v2, v14, 16, 1
	v_add3_u32 v2, v14, v2, s65
	s_waitcnt lgkmcnt(2)
	v_bfe_u32 v3, v88, 16, 1
	v_lshrrev_b32_e32 v2, 16, v2
	v_add3_u32 v3, v88, v3, s65
	v_and_or_b32 v2, v3, s66, v2
	s_waitcnt lgkmcnt(1)
	v_bfe_u32 v3, v90, 16, 1
	v_add3_u32 v3, v90, v3, s65
	s_waitcnt lgkmcnt(0)
	v_bfe_u32 v4, v112, 16, 1
	v_lshrrev_b32_e32 v3, 16, v3
	v_add3_u32 v4, v112, v4, s65
	v_and_or_b32 v3, v4, s66, v3
	v_or_b32_e32 v4, s1, v55
	v_lshlrev_b32_e32 v18, 10, v4
	v_lshl_add_u64 v[114:115], v[6:7], 0, v[18:19]
	global_store_dwordx4 v[114:115], v[0:3], off nt
	v_bfe_u32 v4, v113, 16, 1
	v_add3_u32 v4, v113, v4, s65
	v_bfe_u32 v0, v5, 16, 1
	v_add3_u32 v0, v5, v0, s65
	v_bfe_u32 v1, v9, 16, 1
	v_lshrrev_b32_e32 v0, 16, v0
	v_add3_u32 v1, v9, v1, s65
	v_and_or_b32 v0, v1, s66, v0
	v_bfe_u32 v1, v11, 16, 1
	v_add3_u32 v1, v11, v1, s65
	v_bfe_u32 v2, v13, 16, 1
	v_lshrrev_b32_e32 v1, 16, v1
	v_add3_u32 v2, v13, v2, s65
	v_and_or_b32 v1, v2, s66, v1
	v_bfe_u32 v2, v15, 16, 1
	v_add3_u32 v2, v15, v2, s65
	v_bfe_u32 v3, v89, 16, 1
	v_lshrrev_b32_e32 v2, 16, v2
	v_add3_u32 v3, v89, v3, s65
	v_and_or_b32 v2, v3, s66, v2
	v_bfe_u32 v3, v91, 16, 1
	v_add3_u32 v3, v91, v3, s65
	v_lshrrev_b32_e32 v3, 16, v3
	v_and_or_b32 v3, v4, s66, v3
	v_or_b32_e32 v4, s1, v57
	v_lshlrev_b32_e32 v18, 10, v4
	v_lshl_add_u64 v[4:5], v[6:7], 0, v[18:19]
	global_store_dwordx4 v[4:5], v[0:3], off nt
	s_waitcnt lgkmcnt(0)

.LBB0_86:
	s_lshl_b32 s24, s5, 1
	s_lshl_b32 s7, s4, 1
	v_or_b32_e32 v75, s24, v54
	s_add_i32 s27, s24, 4
	v_or_b32_e32 v73, s7, v17
	s_add_i32 s26, s7, 4
	s_add_i32 s72, s24, 8
	v_add_lshl_u32 v18, v75, s0, 9
	v_or_b32_e32 v79, s27, v54
	v_mov_b32_e32 v3, v19
	s_add_i32 s74, s24, 12
	v_add_lshl_u32 v2, v73, s3, 9
	v_or_b32_e32 v77, s26, v17
	v_or_b32_e32 v114, s72, v54
	v_lshl_add_u64 v[90:91], v[18:19], 2, v[0:1]
	v_add_lshl_u32 v18, v79, s0, 9
	v_mov_b32_e32 v5, v19
	s_add_i32 s71, s7, 8
	s_add_i32 s73, s7, 12
	s_add_i32 s76, s24, 16
	v_or_b32_e32 v116, s74, v54
	v_lshl_add_u64 v[2:3], v[2:3], 2, v[0:1]
	v_add_lshl_u32 v4, v77, s3, 9
	v_lshl_add_u64 v[112:113], v[18:19], 2, v[0:1]
	v_add_lshl_u32 v18, v114, s0, 9
	s_add_i32 s78, s24, 20
	v_or_b32_e32 v111, s71, v17
	v_or_b32_e32 v115, s73, v17
	v_or_b32_e32 v118, s76, v54
	v_lshl_add_u64 v[4:5], v[4:5], 2, v[0:1]
	global_load_dword v126, v[90:91], off nt
	global_load_dword v127, v[2:3], off nt
	global_load_dword v128, v[112:113], off nt
	global_load_dword v129, v[4:5], off nt
	v_lshl_add_u64 v[2:3], v[18:19], 2, v[0:1]
	v_add_lshl_u32 v18, v116, s0, 9
	v_mov_b32_e32 v7, v19
	v_mov_b32_e32 v9, v19
	s_add_i32 s75, s7, 16
	s_add_i32 s77, s7, 20
	s_add_i32 s80, s24, 24
	v_or_b32_e32 v120, s78, v54
	v_add_lshl_u32 v6, v111, s3, 9
	v_add_lshl_u32 v8, v115, s3, 9
	v_lshl_add_u64 v[4:5], v[18:19], 2, v[0:1]
	v_add_lshl_u32 v18, v118, s0, 9
	s_add_i32 s79, s7, 24
	s_add_i32 s7, s7, 28
	s_add_i32 s24, s24, 28
	v_or_b32_e32 v117, s75, v17
	v_or_b32_e32 v119, s77, v17
	v_or_b32_e32 v122, s80, v54
	v_lshl_add_u64 v[6:7], v[6:7], 2, v[0:1]
	v_lshl_add_u64 v[8:9], v[8:9], 2, v[0:1]
	global_load_dword v130, v[2:3], off nt
	global_load_dword v131, v[6:7], off nt
	global_load_dword v132, v[4:5], off nt
	global_load_dword v133, v[8:9], off nt
	v_lshl_add_u64 v[2:3], v[18:19], 2, v[0:1]
	v_add_lshl_u32 v18, v120, s0, 9
	v_mov_b32_e32 v11, v19
	v_mov_b32_e32 v13, v19
	v_or_b32_e32 v121, s79, v17
	v_or_b32_e32 v124, s7, v17
	v_or_b32_e32 v123, s24, v54
	v_add_lshl_u32 v10, v117, s3, 9
	v_add_lshl_u32 v12, v119, s3, 9
	v_lshl_add_u64 v[4:5], v[18:19], 2, v[0:1]
	v_add_lshl_u32 v18, v122, s0, 9
	v_mov_b32_e32 v15, v19
	v_mov_b32_e32 v89, v19
	v_add_lshl_u32 v14, v121, s3, 9
	v_add_lshl_u32 v88, v124, s3, 9
	v_lshl_add_u64 v[10:11], v[10:11], 2, v[0:1]
	v_lshl_add_u64 v[12:13], v[12:13], 2, v[0:1]
	global_load_dword v134, v[2:3], off nt
	global_load_dword v135, v[10:11], off nt
	global_load_dword v136, v[4:5], off nt
	global_load_dword v137, v[12:13], off nt
	v_lshl_add_u64 v[2:3], v[18:19], 2, v[0:1]
	v_add_lshl_u32 v18, v123, s0, 9
	v_lshl_add_u64 v[14:15], v[14:15], 2, v[0:1]
	v_lshl_add_u64 v[88:89], v[88:89], 2, v[0:1]
	v_lshl_add_u64 v[4:5], v[18:19], 2, v[0:1]
	global_load_dword v18, v[2:3], off nt
	global_load_dword v138, v[14:15], off nt
	global_load_dword v139, v[4:5], off nt
	global_load_dword v140, v[88:89], off nt
	s_add_i32 s5, s5, 16
	s_add_i32 s4, s4, 16
	s_add_i32 s6, s6, -16
	v_mad_u64_u32 v[2:3], s[26:27], v75, s49, v[56:57]
	s_cmp_lg_u32 s6, 0
	v_mad_u64_u32 v[4:5], s[26:27], v73, s49, v[56:57]
	v_mad_u64_u32 v[6:7], s[26:27], v79, s49, v[56:57]
	v_mad_u64_u32 v[8:9], s[26:27], v77, s49, v[56:57]
	v_mad_u64_u32 v[10:11], s[26:27], v114, s49, v[56:57]
	v_mad_u64_u32 v[12:13], s[26:27], v111, s49, v[56:57]
	v_mad_u64_u32 v[14:15], s[26:27], v116, s49, v[56:57]
	v_mad_u64_u32 v[88:89], s[26:27], v115, s49, v[56:57]
	v_mad_u64_u32 v[90:91], s[26:27], v118, s49, v[56:57]
	v_mad_u64_u32 v[112:113], s[26:27], v117, s49, v[56:57]
	v_mad_u64_u32 v[114:115], s[26:27], v120, s49, v[56:57]
	v_mad_u64_u32 v[116:117], s[26:27], v119, s49, v[56:57]
	v_mad_u64_u32 v[118:119], s[26:27], v122, s49, v[56:57]
	v_mad_u64_u32 v[120:121], s[26:27], v121, s49, v[56:57]
	v_mad_u64_u32 v[122:123], s[26:27], v123, s49, v[56:57]
	v_mad_u64_u32 v[124:125], s[26:27], v124, s49, v[56:57]
	s_waitcnt vmcnt(0)
	ds_write_b32 v2, v126
	ds_write_b32 v4, v127
	ds_write_b32 v6, v128
	ds_write_b32 v8, v129
	ds_write_b32 v10, v130
	ds_write_b32 v12, v131
	ds_write_b32 v14, v132
	ds_write_b32 v88, v133
	ds_write_b32 v90, v134
	ds_write_b32 v112, v135
	ds_write_b32 v114, v136
	ds_write_b32 v116, v137
	ds_write_b32 v118, v18
	ds_write_b32 v120, v138
	ds_write_b32 v122, v139
	ds_write_b32 v124, v140
	s_cbranch_scc1 .LBB0_86
	s_waitcnt lgkmcnt(0)
	ds_read2_b32 v[4:5], v94 offset1:8
	ds_read2_b32 v[8:9], v94 offset0:33 offset1:41
	ds_read2_b32 v[10:11], v94 offset0:66 offset1:74
	ds_read2_b32 v[12:13], v94 offset0:99 offset1:107
	ds_read2_b32 v[14:15], v94 offset0:132 offset1:140
	s_waitcnt lgkmcnt(0)
	v_bfe_u32 v0, v4, 16, 1
	v_add3_u32 v0, v4, v0, s65
	v_bfe_u32 v1, v8, 16, 1
	v_lshrrev_b32_e32 v0, 16, v0
	v_add3_u32 v1, v8, v1, s65
	ds_read2_b32 v[88:89], v94 offset0:165 offset1:173
	v_and_or_b32 v0, v1, s66, v0
	v_bfe_u32 v1, v10, 16, 1
	v_add3_u32 v1, v10, v1, s65
	v_bfe_u32 v2, v12, 16, 1
	ds_read2_b32 v[90:91], v94 offset0:198 offset1:206
	s_cmpk_lt_u32 s1, 0x200
	v_lshrrev_b32_e32 v1, 16, v1
	v_add3_u32 v2, v12, v2, s65
	ds_read2_b32 v[112:113], v94 offset0:231 offset1:239
	s_cselect_b64 s[4:5], -1, 0
	v_and_or_b32 v1, v2, s66, v1
	v_bfe_u32 v2, v14, 16, 1
	s_and_b64 s[4:5], s[4:5], exec
	s_mov_b32 s1, 0x11600000
	v_add3_u32 v2, v14, v2, s65
	s_waitcnt lgkmcnt(2)
	v_bfe_u32 v3, v88, 16, 1
	s_cselect_b32 s1, s1, 0x11b00000
	v_lshrrev_b32_e32 v2, 16, v2
	v_add3_u32 v3, v88, v3, s65
	s_cselect_b32 s3, 0x300, 0
	s_add_u32 s1, s28, s1
	v_and_or_b32 v2, v3, s66, v2
	s_waitcnt lgkmcnt(1)
	v_bfe_u32 v3, v90, 16, 1
	s_addc_u32 s4, s29, 0
	s_add_i32 s3, s3, s2
	s_lshl_b32 s0, s0, 1
	v_add3_u32 v3, v90, v3, s65
	s_waitcnt lgkmcnt(0)
	v_bfe_u32 v4, v112, 16, 1
	s_add_u32 s0, s1, s0
	v_lshrrev_b32_e32 v3, 16, v3
	v_add3_u32 v4, v112, v4, s65
	s_addc_u32 s1, s4, 0
	v_lshlrev_b32_e32 v18, 1, v24
	v_and_or_b32 v3, v4, s66, v3
	v_or_b32_e32 v4, s3, v25
	v_lshl_add_u64 v[6:7], s[0:1], 0, v[18:19]
	v_lshlrev_b32_e32 v18, 12, v4
	v_lshl_add_u64 v[114:115], v[6:7], 0, v[18:19]
	global_store_dwordx4 v[114:115], v[0:3], off nt
	v_bfe_u32 v4, v113, 16, 1
	v_or_b32_e32 v8, s3, v33
	v_bfe_u32 v0, v5, 16, 1
	v_add3_u32 v0, v5, v0, s65
	v_bfe_u32 v1, v9, 16, 1
	v_lshrrev_b32_e32 v0, 16, v0
	v_add3_u32 v1, v9, v1, s65
	v_and_or_b32 v0, v1, s66, v0
	v_bfe_u32 v1, v11, 16, 1
	v_add3_u32 v1, v11, v1, s65
	v_bfe_u32 v2, v13, 16, 1
	v_lshrrev_b32_e32 v1, 16, v1
	v_add3_u32 v2, v13, v2, s65
	v_and_or_b32 v1, v2, s66, v1
	v_bfe_u32 v2, v15, 16, 1
	v_add3_u32 v2, v15, v2, s65
	v_bfe_u32 v3, v89, 16, 1
	v_lshrrev_b32_e32 v2, 16, v2
	v_add3_u32 v3, v89, v3, s65
	v_and_or_b32 v2, v3, s66, v2
	v_bfe_u32 v3, v91, 16, 1
	v_add3_u32 v3, v91, v3, s65
	v_lshrrev_b32_e32 v3, 16, v3
	v_add3_u32 v4, v113, v4, s65
	v_lshlrev_b32_e32 v18, 12, v8
	v_and_or_b32 v3, v4, s66, v3
	ds_read2_b32 v[4:5], v94 offset0:16 offset1:24
	v_lshl_add_u64 v[8:9], v[6:7], 0, v[18:19]
	global_store_dwordx4 v[8:9], v[0:3], off nt
	ds_read2_b32 v[8:9], v94 offset0:49 offset1:57
	ds_read2_b32 v[10:11], v94 offset0:82 offset1:90
	ds_read2_b32 v[12:13], v94 offset0:115 offset1:123
	s_waitcnt lgkmcnt(3)
	v_bfe_u32 v0, v4, 16, 1
	v_add3_u32 v0, v4, v0, s65
	s_waitcnt lgkmcnt(2)
	v_bfe_u32 v1, v8, 16, 1
	ds_read2_b32 v[14:15], v94 offset0:148 offset1:156
	v_lshrrev_b32_e32 v0, 16, v0
	v_add3_u32 v1, v8, v1, s65
	ds_read2_b32 v[88:89], v94 offset0:181 offset1:189
	v_and_or_b32 v0, v1, s66, v0
	s_waitcnt lgkmcnt(3)
	v_bfe_u32 v1, v10, 16, 1
	v_add3_u32 v1, v10, v1, s65
	s_waitcnt lgkmcnt(2)
	v_bfe_u32 v2, v12, 16, 1
	ds_read2_b32 v[90:91], v94 offset0:214 offset1:222
	v_lshrrev_b32_e32 v1, 16, v1
	v_add3_u32 v2, v12, v2, s65
	ds_read2_b32 v[112:113], v94 offset0:247 offset1:255
	v_and_or_b32 v1, v2, s66, v1
	s_waitcnt lgkmcnt(3)
	v_bfe_u32 v2, v14, 16, 1
	v_add3_u32 v2, v14, v2, s65
	s_waitcnt lgkmcnt(2)
	v_bfe_u32 v3, v88, 16, 1
	v_lshrrev_b32_e32 v2, 16, v2
	v_add3_u32 v3, v88, v3, s65
	v_and_or_b32 v2, v3, s66, v2
	s_waitcnt lgkmcnt(1)
	v_bfe_u32 v3, v90, 16, 1
	v_add3_u32 v3, v90, v3, s65
	s_waitcnt lgkmcnt(0)
	v_bfe_u32 v4, v112, 16, 1
	v_lshrrev_b32_e32 v3, 16, v3
	v_add3_u32 v4, v112, v4, s65
	v_and_or_b32 v3, v4, s66, v3
	v_or_b32_e32 v4, s3, v55
	v_lshlrev_b32_e32 v18, 12, v4
	v_lshl_add_u64 v[114:115], v[6:7], 0, v[18:19]
	global_store_dwordx4 v[114:115], v[0:3], off nt
	v_bfe_u32 v4, v113, 16, 1
	v_add3_u32 v4, v113, v4, s65
	v_bfe_u32 v0, v5, 16, 1
	v_add3_u32 v0, v5, v0, s65
	v_bfe_u32 v1, v9, 16, 1
	v_lshrrev_b32_e32 v0, 16, v0
	v_add3_u32 v1, v9, v1, s65
	v_and_or_b32 v0, v1, s66, v0
	v_bfe_u32 v1, v11, 16, 1
	v_add3_u32 v1, v11, v1, s65
	v_bfe_u32 v2, v13, 16, 1
	v_lshrrev_b32_e32 v1, 16, v1
	v_add3_u32 v2, v13, v2, s65
	v_and_or_b32 v1, v2, s66, v1
	v_bfe_u32 v2, v15, 16, 1
	v_add3_u32 v2, v15, v2, s65
	v_bfe_u32 v3, v89, 16, 1
	v_lshrrev_b32_e32 v2, 16, v2
	v_add3_u32 v3, v89, v3, s65
	v_and_or_b32 v2, v3, s66, v2
	v_bfe_u32 v3, v91, 16, 1
	v_add3_u32 v3, v91, v3, s65
	v_lshrrev_b32_e32 v3, 16, v3
	v_and_or_b32 v3, v4, s66, v3
	v_or_b32_e32 v4, s3, v57
	v_lshlrev_b32_e32 v18, 12, v4
	v_lshl_add_u64 v[4:5], v[6:7], 0, v[18:19]
	global_store_dwordx4 v[4:5], v[0:3], off nt
	s_waitcnt lgkmcnt(0)

.LBB0_91:
	s_lshl_b32 s6, s3, 1
	s_lshl_b32 s5, s2, 1
	v_or_b32_e32 v75, s6, v54
	s_add_i32 s24, s6, 4
	v_or_b32_e32 v73, s5, v17
	s_add_i32 s7, s5, 4
	s_add_i32 s27, s6, 8
	v_add_lshl_u32 v18, v75, s0, 6
	v_or_b32_e32 v79, s24, v54
	v_mov_b32_e32 v1, v19
	s_add_i32 s72, s6, 12
	v_add_lshl_u32 v0, v73, s1, 6
	v_or_b32_e32 v77, s7, v17
	v_or_b32_e32 v112, s27, v54
	v_lshl_add_u64 v[88:89], v[18:19], 2, v[30:31]
	v_add_lshl_u32 v18, v79, s0, 6
	v_mov_b32_e32 v3, v19
	s_add_i32 s26, s5, 8
	s_add_i32 s71, s5, 12
	s_add_i32 s74, s6, 16
	v_or_b32_e32 v114, s72, v54
	v_lshl_add_u64 v[0:1], v[0:1], 2, v[30:31]
	v_add_lshl_u32 v2, v77, s1, 6
	v_lshl_add_u64 v[90:91], v[18:19], 2, v[30:31]
	v_add_lshl_u32 v18, v112, s0, 6
	s_add_i32 s76, s6, 20
	v_or_b32_e32 v111, s26, v17
	v_or_b32_e32 v113, s71, v17
	v_or_b32_e32 v116, s74, v54
	v_lshl_add_u64 v[2:3], v[2:3], 2, v[30:31]
	global_load_dword v124, v[88:89], off nt
	global_load_dword v125, v[0:1], off nt
	global_load_dword v126, v[90:91], off nt
	global_load_dword v127, v[2:3], off nt
	v_lshl_add_u64 v[0:1], v[18:19], 2, v[30:31]
	v_add_lshl_u32 v18, v114, s0, 6
	v_mov_b32_e32 v5, v19
	v_mov_b32_e32 v7, v19
	s_add_i32 s73, s5, 16
	s_add_i32 s75, s5, 20
	s_add_i32 s78, s6, 24
	v_or_b32_e32 v118, s76, v54
	v_add_lshl_u32 v4, v111, s1, 6
	v_add_lshl_u32 v6, v113, s1, 6
	v_lshl_add_u64 v[2:3], v[18:19], 2, v[30:31]
	v_add_lshl_u32 v18, v116, s0, 6
	s_add_i32 s77, s5, 24
	s_add_i32 s5, s5, 28
	s_add_i32 s6, s6, 28
	v_or_b32_e32 v115, s73, v17
	v_or_b32_e32 v117, s75, v17
	v_or_b32_e32 v120, s78, v54
	v_lshl_add_u64 v[4:5], v[4:5], 2, v[30:31]
	v_lshl_add_u64 v[6:7], v[6:7], 2, v[30:31]
	global_load_dword v128, v[0:1], off nt
	global_load_dword v129, v[4:5], off nt
	global_load_dword v130, v[2:3], off nt
	global_load_dword v131, v[6:7], off nt
	v_lshl_add_u64 v[0:1], v[18:19], 2, v[30:31]
	v_add_lshl_u32 v18, v118, s0, 6
	v_mov_b32_e32 v9, v19
	v_mov_b32_e32 v11, v19
	v_or_b32_e32 v119, s77, v17
	v_or_b32_e32 v122, s5, v17
	v_or_b32_e32 v121, s6, v54
	v_add_lshl_u32 v8, v115, s1, 6
	v_add_lshl_u32 v10, v117, s1, 6
	v_lshl_add_u64 v[2:3], v[18:19], 2, v[30:31]
	v_add_lshl_u32 v18, v120, s0, 6
	v_mov_b32_e32 v13, v19
	v_mov_b32_e32 v15, v19
	v_add_lshl_u32 v12, v119, s1, 6
	v_add_lshl_u32 v14, v122, s1, 6
	v_lshl_add_u64 v[8:9], v[8:9], 2, v[30:31]
	v_lshl_add_u64 v[10:11], v[10:11], 2, v[30:31]
	global_load_dword v132, v[0:1], off nt
	global_load_dword v133, v[8:9], off nt
	global_load_dword v134, v[2:3], off nt
	global_load_dword v135, v[10:11], off nt
	v_lshl_add_u64 v[0:1], v[18:19], 2, v[30:31]
	v_add_lshl_u32 v18, v121, s0, 6
	v_lshl_add_u64 v[12:13], v[12:13], 2, v[30:31]
	v_lshl_add_u64 v[14:15], v[14:15], 2, v[30:31]
	v_lshl_add_u64 v[2:3], v[18:19], 2, v[30:31]
	global_load_dword v18, v[0:1], off nt
	global_load_dword v136, v[12:13], off nt
	global_load_dword v137, v[2:3], off nt
	global_load_dword v138, v[14:15], off nt
	s_add_i32 s3, s3, 16
	s_add_i32 s2, s2, 16
	s_add_i32 s4, s4, -16
	v_mad_u64_u32 v[0:1], s[6:7], v75, s49, v[56:57]
	s_cmp_lg_u32 s4, 0
	v_mad_u64_u32 v[2:3], s[6:7], v73, s49, v[56:57]
	v_mad_u64_u32 v[4:5], s[6:7], v79, s49, v[56:57]
	v_mad_u64_u32 v[6:7], s[6:7], v77, s49, v[56:57]
	v_mad_u64_u32 v[8:9], s[6:7], v112, s49, v[56:57]
	v_mad_u64_u32 v[10:11], s[6:7], v111, s49, v[56:57]
	v_mad_u64_u32 v[12:13], s[6:7], v114, s49, v[56:57]
	v_mad_u64_u32 v[14:15], s[6:7], v113, s49, v[56:57]
	v_mad_u64_u32 v[88:89], s[6:7], v116, s49, v[56:57]
	v_mad_u64_u32 v[90:91], s[6:7], v115, s49, v[56:57]
	v_mad_u64_u32 v[112:113], s[6:7], v118, s49, v[56:57]
	v_mad_u64_u32 v[114:115], s[6:7], v117, s49, v[56:57]
	v_mad_u64_u32 v[116:117], s[6:7], v120, s49, v[56:57]
	v_mad_u64_u32 v[118:119], s[6:7], v119, s49, v[56:57]
	v_mad_u64_u32 v[120:121], s[6:7], v121, s49, v[56:57]
	v_mad_u64_u32 v[122:123], s[6:7], v122, s49, v[56:57]
	s_waitcnt vmcnt(0)
	ds_write_b32 v0, v124
	ds_write_b32 v2, v125
	ds_write_b32 v4, v126
	ds_write_b32 v6, v127
	ds_write_b32 v8, v128
	ds_write_b32 v10, v129
	ds_write_b32 v12, v130
	ds_write_b32 v14, v131
	ds_write_b32 v88, v132
	ds_write_b32 v90, v133
	ds_write_b32 v112, v134
	ds_write_b32 v114, v135
	ds_write_b32 v116, v18
	ds_write_b32 v118, v136
	ds_write_b32 v120, v137
	ds_write_b32 v122, v138
	s_cbranch_scc1 .LBB0_91
	s_waitcnt lgkmcnt(0)
	ds_read2_b32 v[4:5], v94 offset1:8
	ds_read2_b32 v[8:9], v94 offset0:33 offset1:41
	ds_read2_b32 v[10:11], v94 offset0:66 offset1:74
	ds_read2_b32 v[12:13], v94 offset0:99 offset1:107
	ds_read2_b32 v[14:15], v94 offset0:132 offset1:140
	ds_read2_b32 v[88:89], v94 offset0:165 offset1:173
	s_waitcnt lgkmcnt(0)
	v_bfe_u32 v0, v4, 16, 1
	v_add3_u32 v0, v4, v0, s65
	v_bfe_u32 v1, v8, 16, 1
	v_lshrrev_b32_e32 v0, 16, v0
	v_add3_u32 v1, v8, v1, s65
	v_and_or_b32 v0, v1, s66, v0
	v_bfe_u32 v1, v10, 16, 1
	v_add3_u32 v1, v10, v1, s65
	v_bfe_u32 v2, v12, 16, 1
	ds_read2_b32 v[90:91], v94 offset0:198 offset1:206
	v_lshrrev_b32_e32 v1, 16, v1
	v_add3_u32 v2, v12, v2, s65
	ds_read2_b32 v[112:113], v94 offset0:231 offset1:239
	v_and_or_b32 v1, v2, s66, v1
	v_bfe_u32 v2, v14, 16, 1
	v_add3_u32 v2, v14, v2, s65
	v_bfe_u32 v3, v88, 16, 1
	v_lshrrev_b32_e32 v2, 16, v2
	v_add3_u32 v3, v88, v3, s65
	v_and_or_b32 v2, v3, s66, v2
	s_waitcnt lgkmcnt(1)
	v_bfe_u32 v3, v90, 16, 1
	s_mov_b32 s1, s25
	v_add3_u32 v3, v90, v3, s65
	s_waitcnt lgkmcnt(0)
	v_bfe_u32 v4, v112, 16, 1
	v_lshl_add_u64 v[6:7], s[0:1], 1, v[60:61]
	v_lshrrev_b32_e32 v3, 16, v3
	v_add3_u32 v4, v112, v4, s65
	v_mov_b32_e32 v73, v19
	v_and_or_b32 v3, v4, s66, v3
	v_lshl_add_u64 v[114:115], v[6:7], 0, v[72:73]
	global_store_dwordx4 v[114:115], v[0:3], off nt
	v_bfe_u32 v4, v113, 16, 1
	v_add3_u32 v4, v113, v4, s65
	v_bfe_u32 v0, v5, 16, 1
	v_add3_u32 v0, v5, v0, s65
	v_bfe_u32 v1, v9, 16, 1
	v_lshrrev_b32_e32 v0, 16, v0
	v_add3_u32 v1, v9, v1, s65
	v_and_or_b32 v0, v1, s66, v0
	v_bfe_u32 v1, v11, 16, 1
	v_add3_u32 v1, v11, v1, s65
	v_bfe_u32 v2, v13, 16, 1
	v_lshrrev_b32_e32 v1, 16, v1
	v_add3_u32 v2, v13, v2, s65
	v_and_or_b32 v1, v2, s66, v1
	v_bfe_u32 v2, v15, 16, 1
	v_add3_u32 v2, v15, v2, s65
	v_bfe_u32 v3, v89, 16, 1
	v_lshrrev_b32_e32 v2, 16, v2
	v_add3_u32 v3, v89, v3, s65
	v_and_or_b32 v2, v3, s66, v2
	v_bfe_u32 v3, v91, 16, 1
	v_add3_u32 v3, v91, v3, s65
	v_lshrrev_b32_e32 v3, 16, v3
	v_mov_b32_e32 v75, v19
	v_and_or_b32 v3, v4, s66, v3
	ds_read2_b32 v[4:5], v94 offset0:16 offset1:24
	v_lshl_add_u64 v[8:9], v[6:7], 0, v[74:75]
	global_store_dwordx4 v[8:9], v[0:3], off nt
	ds_read2_b32 v[8:9], v94 offset0:49 offset1:57
	ds_read2_b32 v[10:11], v94 offset0:82 offset1:90
	ds_read2_b32 v[12:13], v94 offset0:115 offset1:123
	s_waitcnt lgkmcnt(3)
	v_bfe_u32 v0, v4, 16, 1
	v_add3_u32 v0, v4, v0, s65
	s_waitcnt lgkmcnt(2)
	v_bfe_u32 v1, v8, 16, 1
	ds_read2_b32 v[14:15], v94 offset0:148 offset1:156
	v_lshrrev_b32_e32 v0, 16, v0
	v_add3_u32 v1, v8, v1, s65
	ds_read2_b32 v[88:89], v94 offset0:181 offset1:189
	v_and_or_b32 v0, v1, s66, v0
	s_waitcnt lgkmcnt(3)
	v_bfe_u32 v1, v10, 16, 1
	v_add3_u32 v1, v10, v1, s65
	s_waitcnt lgkmcnt(2)
	v_bfe_u32 v2, v12, 16, 1
	ds_read2_b32 v[90:91], v94 offset0:214 offset1:222
	v_lshrrev_b32_e32 v1, 16, v1
	v_add3_u32 v2, v12, v2, s65
	ds_read2_b32 v[112:113], v94 offset0:247 offset1:255
	v_and_or_b32 v1, v2, s66, v1
	s_waitcnt lgkmcnt(3)
	v_bfe_u32 v2, v14, 16, 1
	v_add3_u32 v2, v14, v2, s65
	s_waitcnt lgkmcnt(2)
	v_bfe_u32 v3, v88, 16, 1
	v_lshrrev_b32_e32 v2, 16, v2
	v_add3_u32 v3, v88, v3, s65
	v_and_or_b32 v2, v3, s66, v2
	s_waitcnt lgkmcnt(1)
	v_bfe_u32 v3, v90, 16, 1
	v_add3_u32 v3, v90, v3, s65
	s_waitcnt lgkmcnt(0)
	v_bfe_u32 v4, v112, 16, 1
	v_lshrrev_b32_e32 v3, 16, v3
	v_add3_u32 v4, v112, v4, s65
	v_mov_b32_e32 v77, v19
	v_and_or_b32 v3, v4, s66, v3
	v_lshl_add_u64 v[114:115], v[6:7], 0, v[76:77]
	global_store_dwordx4 v[114:115], v[0:3], off nt
	v_bfe_u32 v4, v113, 16, 1
	v_add3_u32 v4, v113, v4, s65
	v_bfe_u32 v0, v5, 16, 1
	v_add3_u32 v0, v5, v0, s65
	v_bfe_u32 v1, v9, 16, 1
	v_lshrrev_b32_e32 v0, 16, v0
	v_add3_u32 v1, v9, v1, s65
	v_and_or_b32 v0, v1, s66, v0
	v_bfe_u32 v1, v11, 16, 1
	v_add3_u32 v1, v11, v1, s65
	v_bfe_u32 v2, v13, 16, 1
	v_lshrrev_b32_e32 v1, 16, v1
	v_add3_u32 v2, v13, v2, s65
	v_and_or_b32 v1, v2, s66, v1
	v_bfe_u32 v2, v15, 16, 1
	v_add3_u32 v2, v15, v2, s65
	v_bfe_u32 v3, v89, 16, 1
	v_lshrrev_b32_e32 v2, 16, v2
	v_add3_u32 v3, v89, v3, s65
	v_and_or_b32 v2, v3, s66, v2
	v_bfe_u32 v3, v91, 16, 1
	v_add3_u32 v3, v91, v3, s65
	v_lshrrev_b32_e32 v3, 16, v3
	v_mov_b32_e32 v79, v19
	v_and_or_b32 v3, v4, s66, v3
	v_lshl_add_u64 v[4:5], v[6:7], 0, v[78:79]
	global_store_dwordx4 v[4:5], v[0:3], off nt
	s_waitcnt lgkmcnt(0)

.LBB0_96:
	s_lshl_b32 s7, s4, 1
	s_lshl_b32 s6, s3, 1
	v_or_b32_e32 v75, s7, v54
	s_add_i32 s26, s7, 4
	v_or_b32_e32 v73, s6, v17
	s_add_i32 s24, s6, 4
	s_add_i32 s71, s7, 8
	v_add_lshl_u32 v18, v75, s0, 9
	v_or_b32_e32 v79, s26, v54
	v_mov_b32_e32 v3, v19
	s_add_i32 s73, s7, 12
	v_add_lshl_u32 v2, v73, s1, 9
	v_or_b32_e32 v77, s24, v17
	v_or_b32_e32 v114, s71, v54
	v_lshl_add_u64 v[90:91], v[18:19], 2, v[0:1]
	v_add_lshl_u32 v18, v79, s0, 9
	v_mov_b32_e32 v5, v19
	s_add_i32 s27, s6, 8
	s_add_i32 s72, s6, 12
	s_add_i32 s75, s7, 16
	v_or_b32_e32 v116, s73, v54
	v_lshl_add_u64 v[2:3], v[2:3], 2, v[0:1]
	v_add_lshl_u32 v4, v77, s1, 9
	v_lshl_add_u64 v[112:113], v[18:19], 2, v[0:1]
	v_add_lshl_u32 v18, v114, s0, 9
	s_add_i32 s77, s7, 20
	v_or_b32_e32 v111, s27, v17
	v_or_b32_e32 v115, s72, v17
	v_or_b32_e32 v118, s75, v54
	v_lshl_add_u64 v[4:5], v[4:5], 2, v[0:1]
	global_load_dword v126, v[90:91], off nt
	global_load_dword v127, v[2:3], off nt
	global_load_dword v128, v[112:113], off nt
	global_load_dword v129, v[4:5], off nt
	v_lshl_add_u64 v[2:3], v[18:19], 2, v[0:1]
	v_add_lshl_u32 v18, v116, s0, 9
	v_mov_b32_e32 v7, v19
	v_mov_b32_e32 v9, v19
	s_add_i32 s74, s6, 16
	s_add_i32 s76, s6, 20
	s_add_i32 s79, s7, 24
	v_or_b32_e32 v120, s77, v54
	v_add_lshl_u32 v6, v111, s1, 9
	v_add_lshl_u32 v8, v115, s1, 9
	v_lshl_add_u64 v[4:5], v[18:19], 2, v[0:1]
	v_add_lshl_u32 v18, v118, s0, 9
	s_add_i32 s78, s6, 24
	s_add_i32 s6, s6, 28
	s_add_i32 s7, s7, 28
	v_or_b32_e32 v117, s74, v17
	v_or_b32_e32 v119, s76, v17
	v_or_b32_e32 v122, s79, v54
	v_lshl_add_u64 v[6:7], v[6:7], 2, v[0:1]
	v_lshl_add_u64 v[8:9], v[8:9], 2, v[0:1]
	global_load_dword v130, v[2:3], off nt
	global_load_dword v131, v[6:7], off nt
	global_load_dword v132, v[4:5], off nt
	global_load_dword v133, v[8:9], off nt
	v_lshl_add_u64 v[2:3], v[18:19], 2, v[0:1]
	v_add_lshl_u32 v18, v120, s0, 9
	v_mov_b32_e32 v11, v19
	v_mov_b32_e32 v13, v19
	v_or_b32_e32 v121, s78, v17
	v_or_b32_e32 v124, s6, v17
	v_or_b32_e32 v123, s7, v54
	v_add_lshl_u32 v10, v117, s1, 9
	v_add_lshl_u32 v12, v119, s1, 9
	v_lshl_add_u64 v[4:5], v[18:19], 2, v[0:1]
	v_add_lshl_u32 v18, v122, s0, 9
	v_mov_b32_e32 v15, v19
	v_mov_b32_e32 v89, v19
	v_add_lshl_u32 v14, v121, s1, 9
	v_add_lshl_u32 v88, v124, s1, 9
	v_lshl_add_u64 v[10:11], v[10:11], 2, v[0:1]
	v_lshl_add_u64 v[12:13], v[12:13], 2, v[0:1]
	global_load_dword v134, v[2:3], off nt
	global_load_dword v135, v[10:11], off nt
	global_load_dword v136, v[4:5], off nt
	global_load_dword v137, v[12:13], off nt
	v_lshl_add_u64 v[2:3], v[18:19], 2, v[0:1]
	v_add_lshl_u32 v18, v123, s0, 9
	v_lshl_add_u64 v[14:15], v[14:15], 2, v[0:1]
	v_lshl_add_u64 v[88:89], v[88:89], 2, v[0:1]
	v_lshl_add_u64 v[4:5], v[18:19], 2, v[0:1]
	global_load_dword v18, v[2:3], off nt
	global_load_dword v138, v[14:15], off nt
	global_load_dword v139, v[4:5], off nt
	global_load_dword v140, v[88:89], off nt
	s_add_i32 s4, s4, 16
	s_add_i32 s3, s3, 16
	s_add_i32 s5, s5, -16
	v_mad_u64_u32 v[2:3], s[6:7], v75, s49, v[56:57]
	s_cmp_lg_u32 s5, 0
	v_mad_u64_u32 v[4:5], s[6:7], v73, s49, v[56:57]
	v_mad_u64_u32 v[6:7], s[6:7], v79, s49, v[56:57]
	v_mad_u64_u32 v[8:9], s[6:7], v77, s49, v[56:57]
	v_mad_u64_u32 v[10:11], s[6:7], v114, s49, v[56:57]
	v_mad_u64_u32 v[12:13], s[6:7], v111, s49, v[56:57]
	v_mad_u64_u32 v[14:15], s[6:7], v116, s49, v[56:57]
	v_mad_u64_u32 v[88:89], s[6:7], v115, s49, v[56:57]
	v_mad_u64_u32 v[90:91], s[6:7], v118, s49, v[56:57]
	v_mad_u64_u32 v[112:113], s[6:7], v117, s49, v[56:57]
	v_mad_u64_u32 v[114:115], s[6:7], v120, s49, v[56:57]
	v_mad_u64_u32 v[116:117], s[6:7], v119, s49, v[56:57]
	v_mad_u64_u32 v[118:119], s[6:7], v122, s49, v[56:57]
	v_mad_u64_u32 v[120:121], s[6:7], v121, s49, v[56:57]
	v_mad_u64_u32 v[122:123], s[6:7], v123, s49, v[56:57]
	v_mad_u64_u32 v[124:125], s[6:7], v124, s49, v[56:57]
	s_waitcnt vmcnt(0)
	ds_write_b32 v2, v126
	ds_write_b32 v4, v127
	ds_write_b32 v6, v128
	ds_write_b32 v8, v129
	ds_write_b32 v10, v130
	ds_write_b32 v12, v131
	ds_write_b32 v14, v132
	ds_write_b32 v88, v133
	ds_write_b32 v90, v134
	ds_write_b32 v112, v135
	ds_write_b32 v114, v136
	ds_write_b32 v116, v137
	ds_write_b32 v118, v18
	ds_write_b32 v120, v138
	ds_write_b32 v122, v139
	ds_write_b32 v124, v140
	s_cbranch_scc1 .LBB0_96
	s_waitcnt lgkmcnt(0)
	ds_read2_b32 v[4:5], v94 offset1:8
	ds_read2_b32 v[8:9], v94 offset0:33 offset1:41
	ds_read2_b32 v[10:11], v94 offset0:66 offset1:74
	ds_read2_b32 v[12:13], v94 offset0:99 offset1:107
	ds_read2_b32 v[14:15], v94 offset0:132 offset1:140
	ds_read2_b32 v[88:89], v94 offset0:165 offset1:173
	s_waitcnt lgkmcnt(0)
	v_bfe_u32 v0, v4, 16, 1
	v_add3_u32 v0, v4, v0, s65
	v_bfe_u32 v1, v8, 16, 1
	v_lshrrev_b32_e32 v0, 16, v0
	v_add3_u32 v1, v8, v1, s65
	v_and_or_b32 v0, v1, s66, v0
	v_bfe_u32 v1, v10, 16, 1
	v_add3_u32 v1, v10, v1, s65
	v_bfe_u32 v2, v12, 16, 1
	ds_read2_b32 v[90:91], v94 offset0:198 offset1:206
	v_lshrrev_b32_e32 v1, 16, v1
	v_add3_u32 v2, v12, v2, s65
	ds_read2_b32 v[112:113], v94 offset0:231 offset1:239
	v_and_or_b32 v1, v2, s66, v1
	v_bfe_u32 v2, v14, 16, 1
	v_add3_u32 v2, v14, v2, s65
	v_bfe_u32 v3, v88, 16, 1
	v_lshrrev_b32_e32 v2, 16, v2
	v_add3_u32 v3, v88, v3, s65
	v_and_or_b32 v2, v3, s66, v2
	s_waitcnt lgkmcnt(1)
	v_bfe_u32 v3, v90, 16, 1
	v_add3_u32 v3, v90, v3, s65
	s_waitcnt lgkmcnt(0)
	v_bfe_u32 v4, v112, 16, 1
	v_lshrrev_b32_e32 v3, 16, v3
	v_add3_u32 v4, v112, v4, s65
	s_mov_b32 s1, s25
	v_and_or_b32 v3, v4, s66, v3
	v_or_b32_e32 v4, s2, v25
	v_lshl_add_u64 v[6:7], s[0:1], 1, v[60:61]
	v_lshlrev_b32_e32 v18, 12, v4
	v_lshl_add_u64 v[114:115], v[6:7], 0, v[18:19]
	global_store_dwordx4 v[114:115], v[0:3], off nt
	v_bfe_u32 v4, v113, 16, 1
	v_or_b32_e32 v8, s2, v33
	v_bfe_u32 v0, v5, 16, 1
	v_add3_u32 v0, v5, v0, s65
	v_bfe_u32 v1, v9, 16, 1
	v_lshrrev_b32_e32 v0, 16, v0
	v_add3_u32 v1, v9, v1, s65
	v_and_or_b32 v0, v1, s66, v0
	v_bfe_u32 v1, v11, 16, 1
	v_add3_u32 v1, v11, v1, s65
	v_bfe_u32 v2, v13, 16, 1
	v_lshrrev_b32_e32 v1, 16, v1
	v_add3_u32 v2, v13, v2, s65
	v_and_or_b32 v1, v2, s66, v1
	v_bfe_u32 v2, v15, 16, 1
	v_add3_u32 v2, v15, v2, s65
	v_bfe_u32 v3, v89, 16, 1
	v_lshrrev_b32_e32 v2, 16, v2
	v_add3_u32 v3, v89, v3, s65
	v_and_or_b32 v2, v3, s66, v2
	v_bfe_u32 v3, v91, 16, 1
	v_add3_u32 v3, v91, v3, s65
	v_lshrrev_b32_e32 v3, 16, v3
	v_add3_u32 v4, v113, v4, s65
	v_lshlrev_b32_e32 v18, 12, v8
	v_and_or_b32 v3, v4, s66, v3
	ds_read2_b32 v[4:5], v94 offset0:16 offset1:24
	v_lshl_add_u64 v[8:9], v[6:7], 0, v[18:19]
	global_store_dwordx4 v[8:9], v[0:3], off nt
	ds_read2_b32 v[8:9], v94 offset0:49 offset1:57
	ds_read2_b32 v[10:11], v94 offset0:82 offset1:90
	ds_read2_b32 v[12:13], v94 offset0:115 offset1:123
	s_waitcnt lgkmcnt(3)
	v_bfe_u32 v0, v4, 16, 1
	v_add3_u32 v0, v4, v0, s65
	s_waitcnt lgkmcnt(2)
	v_bfe_u32 v1, v8, 16, 1
	ds_read2_b32 v[14:15], v94 offset0:148 offset1:156
	v_lshrrev_b32_e32 v0, 16, v0
	v_add3_u32 v1, v8, v1, s65
	ds_read2_b32 v[88:89], v94 offset0:181 offset1:189
	v_and_or_b32 v0, v1, s66, v0
	s_waitcnt lgkmcnt(3)
	v_bfe_u32 v1, v10, 16, 1
	v_add3_u32 v1, v10, v1, s65
	s_waitcnt lgkmcnt(2)
	v_bfe_u32 v2, v12, 16, 1
	ds_read2_b32 v[90:91], v94 offset0:214 offset1:222
	v_lshrrev_b32_e32 v1, 16, v1
	v_add3_u32 v2, v12, v2, s65
	ds_read2_b32 v[112:113], v94 offset0:247 offset1:255
	v_and_or_b32 v1, v2, s66, v1
	s_waitcnt lgkmcnt(3)
	v_bfe_u32 v2, v14, 16, 1
	v_add3_u32 v2, v14, v2, s65
	s_waitcnt lgkmcnt(2)
	v_bfe_u32 v3, v88, 16, 1
	v_lshrrev_b32_e32 v2, 16, v2
	v_add3_u32 v3, v88, v3, s65
	v_and_or_b32 v2, v3, s66, v2
	s_waitcnt lgkmcnt(1)
	v_bfe_u32 v3, v90, 16, 1
	v_add3_u32 v3, v90, v3, s65
	s_waitcnt lgkmcnt(0)
	v_bfe_u32 v4, v112, 16, 1
	v_lshrrev_b32_e32 v3, 16, v3
	v_add3_u32 v4, v112, v4, s65
	v_and_or_b32 v3, v4, s66, v3
	v_or_b32_e32 v4, s2, v55
	v_lshlrev_b32_e32 v18, 12, v4
	v_lshl_add_u64 v[114:115], v[6:7], 0, v[18:19]
	global_store_dwordx4 v[114:115], v[0:3], off nt
	v_bfe_u32 v4, v113, 16, 1
	v_add3_u32 v4, v113, v4, s65
	v_bfe_u32 v0, v5, 16, 1
	v_add3_u32 v0, v5, v0, s65
	v_bfe_u32 v1, v9, 16, 1
	v_lshrrev_b32_e32 v0, 16, v0
	v_add3_u32 v1, v9, v1, s65
	v_and_or_b32 v0, v1, s66, v0
	v_bfe_u32 v1, v11, 16, 1
	v_add3_u32 v1, v11, v1, s65
	v_bfe_u32 v2, v13, 16, 1
	v_lshrrev_b32_e32 v1, 16, v1
	v_add3_u32 v2, v13, v2, s65
	v_and_or_b32 v1, v2, s66, v1
	v_bfe_u32 v2, v15, 16, 1
	v_add3_u32 v2, v15, v2, s65
	v_bfe_u32 v3, v89, 16, 1
	v_lshrrev_b32_e32 v2, 16, v2
	v_add3_u32 v3, v89, v3, s65
	v_and_or_b32 v2, v3, s66, v2
	v_bfe_u32 v3, v91, 16, 1
	v_add3_u32 v3, v91, v3, s65
	v_lshrrev_b32_e32 v3, 16, v3
	v_and_or_b32 v3, v4, s66, v3
	v_or_b32_e32 v4, s2, v57
	v_lshlrev_b32_e32 v18, 12, v4
	v_lshl_add_u64 v[4:5], v[6:7], 0, v[18:19]
	global_store_dwordx4 v[4:5], v[0:3], off nt
	s_waitcnt lgkmcnt(0)

.LBB0_101:
	s_lshl_b32 s26, s5, 1
	s_lshl_b32 s7, s4, 1
	v_or_b32_e32 v75, s26, v54
	s_add_i32 s71, s26, 4
	v_or_b32_e32 v73, s7, v17
	s_add_i32 s27, s7, 4
	s_add_i32 s73, s26, 8
	v_add_lshl_u32 v18, v75, s0, 9
	v_or_b32_e32 v79, s71, v54
	v_mov_b32_e32 v3, v19
	s_add_i32 s75, s26, 12
	v_add_lshl_u32 v2, v73, s3, 9
	v_or_b32_e32 v77, s27, v17
	v_or_b32_e32 v114, s73, v54
	v_lshl_add_u64 v[90:91], v[18:19], 2, v[0:1]
	v_add_lshl_u32 v18, v79, s0, 9
	v_mov_b32_e32 v5, v19
	s_add_i32 s72, s7, 8
	s_add_i32 s74, s7, 12
	s_add_i32 s77, s26, 16
	v_or_b32_e32 v116, s75, v54
	v_lshl_add_u64 v[2:3], v[2:3], 2, v[0:1]
	v_add_lshl_u32 v4, v77, s3, 9
	v_lshl_add_u64 v[112:113], v[18:19], 2, v[0:1]
	v_add_lshl_u32 v18, v114, s0, 9
	s_add_i32 s79, s26, 20
	v_or_b32_e32 v111, s72, v17
	v_or_b32_e32 v115, s74, v17
	v_or_b32_e32 v118, s77, v54
	v_lshl_add_u64 v[4:5], v[4:5], 2, v[0:1]
	global_load_dword v126, v[90:91], off nt
	global_load_dword v127, v[2:3], off nt
	global_load_dword v128, v[112:113], off nt
	global_load_dword v129, v[4:5], off nt
	v_lshl_add_u64 v[2:3], v[18:19], 2, v[0:1]
	v_add_lshl_u32 v18, v116, s0, 9
	v_mov_b32_e32 v7, v19
	v_mov_b32_e32 v9, v19
	s_add_i32 s76, s7, 16
	s_add_i32 s78, s7, 20
	s_add_i32 s81, s26, 24
	v_or_b32_e32 v120, s79, v54
	v_add_lshl_u32 v6, v111, s3, 9
	v_add_lshl_u32 v8, v115, s3, 9
	v_lshl_add_u64 v[4:5], v[18:19], 2, v[0:1]
	v_add_lshl_u32 v18, v118, s0, 9
	s_add_i32 s80, s7, 24
	s_add_i32 s7, s7, 28
	s_add_i32 s26, s26, 28
	v_or_b32_e32 v117, s76, v17
	v_or_b32_e32 v119, s78, v17
	v_or_b32_e32 v122, s81, v54
	v_lshl_add_u64 v[6:7], v[6:7], 2, v[0:1]
	v_lshl_add_u64 v[8:9], v[8:9], 2, v[0:1]
	global_load_dword v130, v[2:3], off nt
	global_load_dword v131, v[6:7], off nt
	global_load_dword v132, v[4:5], off nt
	global_load_dword v133, v[8:9], off nt
	v_lshl_add_u64 v[2:3], v[18:19], 2, v[0:1]
	v_add_lshl_u32 v18, v120, s0, 9
	v_mov_b32_e32 v11, v19
	v_mov_b32_e32 v13, v19
	v_or_b32_e32 v121, s80, v17
	v_or_b32_e32 v124, s7, v17
	v_or_b32_e32 v123, s26, v54
	v_add_lshl_u32 v10, v117, s3, 9
	v_add_lshl_u32 v12, v119, s3, 9
	v_lshl_add_u64 v[4:5], v[18:19], 2, v[0:1]
	v_add_lshl_u32 v18, v122, s0, 9
	v_mov_b32_e32 v15, v19
	v_mov_b32_e32 v89, v19
	v_add_lshl_u32 v14, v121, s3, 9
	v_add_lshl_u32 v88, v124, s3, 9
	v_lshl_add_u64 v[10:11], v[10:11], 2, v[0:1]
	v_lshl_add_u64 v[12:13], v[12:13], 2, v[0:1]
	global_load_dword v134, v[2:3], off nt
	global_load_dword v135, v[10:11], off nt
	global_load_dword v136, v[4:5], off nt
	global_load_dword v137, v[12:13], off nt
	v_lshl_add_u64 v[2:3], v[18:19], 2, v[0:1]
	v_add_lshl_u32 v18, v123, s0, 9
	v_lshl_add_u64 v[14:15], v[14:15], 2, v[0:1]
	v_lshl_add_u64 v[88:89], v[88:89], 2, v[0:1]
	v_lshl_add_u64 v[4:5], v[18:19], 2, v[0:1]
	global_load_dword v18, v[2:3], off nt
	global_load_dword v138, v[14:15], off nt
	global_load_dword v139, v[4:5], off nt
	global_load_dword v140, v[88:89], off nt
	s_add_i32 s5, s5, 16
	s_add_i32 s4, s4, 16
	s_add_i32 s6, s6, -16
	v_mad_u64_u32 v[2:3], s[26:27], v75, s49, v[56:57]
	s_cmp_lg_u32 s6, 0
	v_mad_u64_u32 v[4:5], s[26:27], v73, s49, v[56:57]
	v_mad_u64_u32 v[6:7], s[26:27], v79, s49, v[56:57]
	v_mad_u64_u32 v[8:9], s[26:27], v77, s49, v[56:57]
	v_mad_u64_u32 v[10:11], s[26:27], v114, s49, v[56:57]
	v_mad_u64_u32 v[12:13], s[26:27], v111, s49, v[56:57]
	v_mad_u64_u32 v[14:15], s[26:27], v116, s49, v[56:57]
	v_mad_u64_u32 v[88:89], s[26:27], v115, s49, v[56:57]
	v_mad_u64_u32 v[90:91], s[26:27], v118, s49, v[56:57]
	v_mad_u64_u32 v[112:113], s[26:27], v117, s49, v[56:57]
	v_mad_u64_u32 v[114:115], s[26:27], v120, s49, v[56:57]
	v_mad_u64_u32 v[116:117], s[26:27], v119, s49, v[56:57]
	v_mad_u64_u32 v[118:119], s[26:27], v122, s49, v[56:57]
	v_mad_u64_u32 v[120:121], s[26:27], v121, s49, v[56:57]
	v_mad_u64_u32 v[122:123], s[26:27], v123, s49, v[56:57]
	v_mad_u64_u32 v[124:125], s[26:27], v124, s49, v[56:57]
	s_waitcnt vmcnt(0)
	ds_write_b32 v2, v126
	ds_write_b32 v4, v127
	ds_write_b32 v6, v128
	ds_write_b32 v8, v129
	ds_write_b32 v10, v130
	ds_write_b32 v12, v131
	ds_write_b32 v14, v132
	ds_write_b32 v88, v133
	ds_write_b32 v90, v134
	ds_write_b32 v112, v135
	ds_write_b32 v114, v136
	ds_write_b32 v116, v137
	ds_write_b32 v118, v18
	ds_write_b32 v120, v138
	ds_write_b32 v122, v139
	ds_write_b32 v124, v140
	s_cbranch_scc1 .LBB0_101
	s_waitcnt lgkmcnt(0)
	ds_read2_b32 v[4:5], v94 offset1:8
	ds_read2_b32 v[8:9], v94 offset0:33 offset1:41
	ds_read2_b32 v[10:11], v94 offset0:66 offset1:74
	ds_read2_b32 v[12:13], v94 offset0:99 offset1:107
	ds_read2_b32 v[14:15], v94 offset0:132 offset1:140
	s_waitcnt lgkmcnt(0)
	v_bfe_u32 v0, v4, 16, 1
	v_add3_u32 v0, v4, v0, s65
	v_bfe_u32 v1, v8, 16, 1
	v_lshrrev_b32_e32 v0, 16, v0
	v_add3_u32 v1, v8, v1, s65
	ds_read2_b32 v[88:89], v94 offset0:165 offset1:173
	v_and_or_b32 v0, v1, s66, v0
	v_bfe_u32 v1, v10, 16, 1
	v_add3_u32 v1, v10, v1, s65
	v_bfe_u32 v2, v12, 16, 1
	ds_read2_b32 v[90:91], v94 offset0:198 offset1:206
	v_lshrrev_b32_e32 v1, 16, v1
	v_add3_u32 v2, v12, v2, s65
	ds_read2_b32 v[112:113], v94 offset0:231 offset1:239
	v_and_or_b32 v1, v2, s66, v1
	v_bfe_u32 v2, v14, 16, 1
	s_lshr_b32 s4, s1, 9
	s_mov_b32 s5, s25
	s_lshl_b32 s1, s24, 9
	v_add3_u32 v2, v14, v2, s65
	s_waitcnt lgkmcnt(2)
	v_bfe_u32 v3, v88, 16, 1
	s_lshl_b64 s[4:5], s[4:5], 21
	s_and_b32 s1, s1, 0x600
	v_lshrrev_b32_e32 v2, 16, v2
	v_add3_u32 v3, v88, v3, s65
	s_add_u32 s3, s40, s4
	v_and_or_b32 v2, v3, s66, v2
	s_waitcnt lgkmcnt(1)
	v_bfe_u32 v3, v90, 16, 1
	s_addc_u32 s4, s41, s5
	s_or_b32 s2, s1, s2
	s_lshl_b32 s0, s0, 1
	v_add3_u32 v3, v90, v3, s65
	s_waitcnt lgkmcnt(0)
	v_bfe_u32 v4, v112, 16, 1
	s_add_u32 s0, s3, s0
	v_lshrrev_b32_e32 v3, 16, v3
	v_add3_u32 v4, v112, v4, s65
	s_addc_u32 s1, s4, 0
	v_lshlrev_b32_e32 v18, 1, v24
	v_and_or_b32 v3, v4, s66, v3
	v_or_b32_e32 v4, s2, v25
	v_lshl_add_u64 v[6:7], s[0:1], 0, v[18:19]
	v_lshlrev_b32_e32 v18, 10, v4
	v_lshl_add_u64 v[114:115], v[6:7], 0, v[18:19]
	global_store_dwordx4 v[114:115], v[0:3], off nt
	v_bfe_u32 v4, v113, 16, 1
	v_or_b32_e32 v8, s2, v33
	v_bfe_u32 v0, v5, 16, 1
	v_add3_u32 v0, v5, v0, s65
	v_bfe_u32 v1, v9, 16, 1
	v_lshrrev_b32_e32 v0, 16, v0
	v_add3_u32 v1, v9, v1, s65
	v_and_or_b32 v0, v1, s66, v0
	v_bfe_u32 v1, v11, 16, 1
	v_add3_u32 v1, v11, v1, s65
	v_bfe_u32 v2, v13, 16, 1
	v_lshrrev_b32_e32 v1, 16, v1
	v_add3_u32 v2, v13, v2, s65
	v_and_or_b32 v1, v2, s66, v1
	v_bfe_u32 v2, v15, 16, 1
	v_add3_u32 v2, v15, v2, s65
	v_bfe_u32 v3, v89, 16, 1
	v_lshrrev_b32_e32 v2, 16, v2
	v_add3_u32 v3, v89, v3, s65
	v_and_or_b32 v2, v3, s66, v2
	v_bfe_u32 v3, v91, 16, 1
	v_add3_u32 v3, v91, v3, s65
	v_lshrrev_b32_e32 v3, 16, v3
	v_add3_u32 v4, v113, v4, s65
	v_lshlrev_b32_e32 v18, 10, v8
	v_and_or_b32 v3, v4, s66, v3
	ds_read2_b32 v[4:5], v94 offset0:16 offset1:24
	v_lshl_add_u64 v[8:9], v[6:7], 0, v[18:19]
	global_store_dwordx4 v[8:9], v[0:3], off nt
	ds_read2_b32 v[8:9], v94 offset0:49 offset1:57
	ds_read2_b32 v[10:11], v94 offset0:82 offset1:90
	ds_read2_b32 v[12:13], v94 offset0:115 offset1:123
	s_waitcnt lgkmcnt(3)
	v_bfe_u32 v0, v4, 16, 1
	v_add3_u32 v0, v4, v0, s65
	s_waitcnt lgkmcnt(2)
	v_bfe_u32 v1, v8, 16, 1
	ds_read2_b32 v[14:15], v94 offset0:148 offset1:156
	v_lshrrev_b32_e32 v0, 16, v0
	v_add3_u32 v1, v8, v1, s65
	ds_read2_b32 v[88:89], v94 offset0:181 offset1:189
	v_and_or_b32 v0, v1, s66, v0
	s_waitcnt lgkmcnt(3)
	v_bfe_u32 v1, v10, 16, 1
	v_add3_u32 v1, v10, v1, s65
	s_waitcnt lgkmcnt(2)
	v_bfe_u32 v2, v12, 16, 1
	ds_read2_b32 v[90:91], v94 offset0:214 offset1:222
	v_lshrrev_b32_e32 v1, 16, v1
	v_add3_u32 v2, v12, v2, s65
	ds_read2_b32 v[112:113], v94 offset0:247 offset1:255
	v_and_or_b32 v1, v2, s66, v1
	s_waitcnt lgkmcnt(3)
	v_bfe_u32 v2, v14, 16, 1
	v_add3_u32 v2, v14, v2, s65
	s_waitcnt lgkmcnt(2)
	v_bfe_u32 v3, v88, 16, 1
	v_lshrrev_b32_e32 v2, 16, v2
	v_add3_u32 v3, v88, v3, s65
	v_and_or_b32 v2, v3, s66, v2
	s_waitcnt lgkmcnt(1)
	v_bfe_u32 v3, v90, 16, 1
	v_add3_u32 v3, v90, v3, s65
	s_waitcnt lgkmcnt(0)
	v_bfe_u32 v4, v112, 16, 1
	v_lshrrev_b32_e32 v3, 16, v3
	v_add3_u32 v4, v112, v4, s65
	v_and_or_b32 v3, v4, s66, v3
	v_or_b32_e32 v4, s2, v55
	v_lshlrev_b32_e32 v18, 10, v4
	v_lshl_add_u64 v[114:115], v[6:7], 0, v[18:19]
	global_store_dwordx4 v[114:115], v[0:3], off nt
	v_bfe_u32 v4, v113, 16, 1
	v_add3_u32 v4, v113, v4, s65
	v_bfe_u32 v0, v5, 16, 1
	v_add3_u32 v0, v5, v0, s65
	v_bfe_u32 v1, v9, 16, 1
	v_lshrrev_b32_e32 v0, 16, v0
	v_add3_u32 v1, v9, v1, s65
	v_and_or_b32 v0, v1, s66, v0
	v_bfe_u32 v1, v11, 16, 1
	v_add3_u32 v1, v11, v1, s65
	v_bfe_u32 v2, v13, 16, 1
	v_lshrrev_b32_e32 v1, 16, v1
	v_add3_u32 v2, v13, v2, s65
	v_and_or_b32 v1, v2, s66, v1
	v_bfe_u32 v2, v15, 16, 1
	v_add3_u32 v2, v15, v2, s65
	v_bfe_u32 v3, v89, 16, 1
	v_lshrrev_b32_e32 v2, 16, v2
	v_add3_u32 v3, v89, v3, s65
	v_and_or_b32 v2, v3, s66, v2
	v_bfe_u32 v3, v91, 16, 1
	v_add3_u32 v3, v91, v3, s65
	v_lshrrev_b32_e32 v3, 16, v3
	v_and_or_b32 v3, v4, s66, v3
	v_or_b32_e32 v4, s2, v57
	v_lshlrev_b32_e32 v18, 10, v4
	v_lshl_add_u64 v[4:5], v[6:7], 0, v[18:19]
	global_store_dwordx4 v[4:5], v[0:3], off nt
	s_waitcnt lgkmcnt(0)

.LBB0_106:
	s_lshl_b32 s24, s5, 1
	s_lshl_b32 s7, s4, 1
	v_or_b32_e32 v75, s24, v54
	s_add_i32 s27, s24, 4
	v_or_b32_e32 v73, s7, v17
	s_add_i32 s26, s7, 4
	s_add_i32 s72, s24, 8
	v_add_lshl_u32 v18, v75, s1, 11
	v_or_b32_e32 v79, s27, v54
	v_mov_b32_e32 v3, v19
	s_add_i32 s74, s24, 12
	v_add_lshl_u32 v2, v73, s3, 11
	v_or_b32_e32 v77, s26, v17
	v_or_b32_e32 v114, s72, v54
	v_lshl_add_u64 v[90:91], v[18:19], 2, v[0:1]
	v_add_lshl_u32 v18, v79, s1, 11
	v_mov_b32_e32 v5, v19
	s_add_i32 s71, s7, 8
	s_add_i32 s73, s7, 12
	s_add_i32 s76, s24, 16
	v_or_b32_e32 v116, s74, v54
	v_lshl_add_u64 v[2:3], v[2:3], 2, v[0:1]
	v_add_lshl_u32 v4, v77, s3, 11
	v_lshl_add_u64 v[112:113], v[18:19], 2, v[0:1]
	v_add_lshl_u32 v18, v114, s1, 11
	s_add_i32 s78, s24, 20
	v_or_b32_e32 v111, s71, v17
	v_or_b32_e32 v115, s73, v17
	v_or_b32_e32 v118, s76, v54
	v_lshl_add_u64 v[4:5], v[4:5], 2, v[0:1]
	global_load_dword v126, v[90:91], off nt
	global_load_dword v127, v[2:3], off nt
	global_load_dword v128, v[112:113], off nt
	global_load_dword v129, v[4:5], off nt
	v_lshl_add_u64 v[2:3], v[18:19], 2, v[0:1]
	v_add_lshl_u32 v18, v116, s1, 11
	v_mov_b32_e32 v7, v19
	v_mov_b32_e32 v9, v19
	s_add_i32 s75, s7, 16
	s_add_i32 s77, s7, 20
	s_add_i32 s80, s24, 24
	v_or_b32_e32 v120, s78, v54
	v_add_lshl_u32 v6, v111, s3, 11
	v_add_lshl_u32 v8, v115, s3, 11
	v_lshl_add_u64 v[4:5], v[18:19], 2, v[0:1]
	v_add_lshl_u32 v18, v118, s1, 11
	s_add_i32 s79, s7, 24
	s_add_i32 s7, s7, 28
	s_add_i32 s24, s24, 28
	v_or_b32_e32 v117, s75, v17
	v_or_b32_e32 v119, s77, v17
	v_or_b32_e32 v122, s80, v54
	v_lshl_add_u64 v[6:7], v[6:7], 2, v[0:1]
	v_lshl_add_u64 v[8:9], v[8:9], 2, v[0:1]
	global_load_dword v130, v[2:3], off nt
	global_load_dword v131, v[6:7], off nt
	global_load_dword v132, v[4:5], off nt
	global_load_dword v133, v[8:9], off nt
	v_lshl_add_u64 v[2:3], v[18:19], 2, v[0:1]
	v_add_lshl_u32 v18, v120, s1, 11
	v_mov_b32_e32 v11, v19
	v_mov_b32_e32 v13, v19
	v_or_b32_e32 v121, s79, v17
	v_or_b32_e32 v124, s7, v17
	v_or_b32_e32 v123, s24, v54
	v_add_lshl_u32 v10, v117, s3, 11
	v_add_lshl_u32 v12, v119, s3, 11
	v_lshl_add_u64 v[4:5], v[18:19], 2, v[0:1]
	v_add_lshl_u32 v18, v122, s1, 11
	v_mov_b32_e32 v15, v19
	v_mov_b32_e32 v89, v19
	v_add_lshl_u32 v14, v121, s3, 11
	v_add_lshl_u32 v88, v124, s3, 11
	v_lshl_add_u64 v[10:11], v[10:11], 2, v[0:1]
	v_lshl_add_u64 v[12:13], v[12:13], 2, v[0:1]
	global_load_dword v134, v[2:3], off nt
	global_load_dword v135, v[10:11], off nt
	global_load_dword v136, v[4:5], off nt
	global_load_dword v137, v[12:13], off nt
	v_lshl_add_u64 v[2:3], v[18:19], 2, v[0:1]
	v_add_lshl_u32 v18, v123, s1, 11
	v_lshl_add_u64 v[14:15], v[14:15], 2, v[0:1]
	v_lshl_add_u64 v[88:89], v[88:89], 2, v[0:1]
	v_lshl_add_u64 v[4:5], v[18:19], 2, v[0:1]
	global_load_dword v18, v[2:3], off nt
	global_load_dword v138, v[14:15], off nt
	global_load_dword v139, v[4:5], off nt
	global_load_dword v140, v[88:89], off nt
	s_add_i32 s5, s5, 16
	s_add_i32 s4, s4, 16
	s_add_i32 s6, s6, -16
	v_mad_u64_u32 v[2:3], s[26:27], v75, s49, v[56:57]
	s_cmp_lg_u32 s6, 0
	v_mad_u64_u32 v[4:5], s[26:27], v73, s49, v[56:57]
	v_mad_u64_u32 v[6:7], s[26:27], v79, s49, v[56:57]
	v_mad_u64_u32 v[8:9], s[26:27], v77, s49, v[56:57]
	v_mad_u64_u32 v[10:11], s[26:27], v114, s49, v[56:57]
	v_mad_u64_u32 v[12:13], s[26:27], v111, s49, v[56:57]
	v_mad_u64_u32 v[14:15], s[26:27], v116, s49, v[56:57]
	v_mad_u64_u32 v[88:89], s[26:27], v115, s49, v[56:57]
	v_mad_u64_u32 v[90:91], s[26:27], v118, s49, v[56:57]
	v_mad_u64_u32 v[112:113], s[26:27], v117, s49, v[56:57]
	v_mad_u64_u32 v[114:115], s[26:27], v120, s49, v[56:57]
	v_mad_u64_u32 v[116:117], s[26:27], v119, s49, v[56:57]
	v_mad_u64_u32 v[118:119], s[26:27], v122, s49, v[56:57]
	v_mad_u64_u32 v[120:121], s[26:27], v121, s49, v[56:57]
	v_mad_u64_u32 v[122:123], s[26:27], v123, s49, v[56:57]
	v_mad_u64_u32 v[124:125], s[26:27], v124, s49, v[56:57]
	s_waitcnt vmcnt(0)
	ds_write_b32 v2, v126
	ds_write_b32 v4, v127
	ds_write_b32 v6, v128
	ds_write_b32 v8, v129
	ds_write_b32 v10, v130
	ds_write_b32 v12, v131
	ds_write_b32 v14, v132
	ds_write_b32 v88, v133
	ds_write_b32 v90, v134
	ds_write_b32 v112, v135
	ds_write_b32 v114, v136
	ds_write_b32 v116, v137
	ds_write_b32 v118, v18
	ds_write_b32 v120, v138
	ds_write_b32 v122, v139
	ds_write_b32 v124, v140
	s_cbranch_scc1 .LBB0_106
	s_waitcnt lgkmcnt(0)
	ds_read2_b32 v[4:5], v94 offset1:8
	ds_read2_b32 v[8:9], v94 offset0:33 offset1:41
	ds_read2_b32 v[10:11], v94 offset0:66 offset1:74
	ds_read2_b32 v[12:13], v94 offset0:99 offset1:107
	ds_read2_b32 v[14:15], v94 offset0:132 offset1:140
	s_waitcnt lgkmcnt(0)
	v_bfe_u32 v0, v4, 16, 1
	v_add3_u32 v0, v4, v0, s65
	v_bfe_u32 v1, v8, 16, 1
	v_lshrrev_b32_e32 v0, 16, v0
	v_add3_u32 v1, v8, v1, s65
	ds_read2_b32 v[88:89], v94 offset0:165 offset1:173
	v_and_or_b32 v0, v1, s66, v0
	v_bfe_u32 v1, v10, 16, 1
	v_add3_u32 v1, v10, v1, s65
	v_bfe_u32 v2, v12, 16, 1
	ds_read2_b32 v[90:91], v94 offset0:198 offset1:206
	v_lshrrev_b32_e32 v1, 16, v1
	v_add3_u32 v2, v12, v2, s65
	ds_read2_b32 v[112:113], v94 offset0:231 offset1:239
	v_and_or_b32 v1, v2, s66, v1
	v_bfe_u32 v2, v14, 16, 1
	v_add3_u32 v2, v14, v2, s65
	s_waitcnt lgkmcnt(2)
	v_bfe_u32 v3, v88, 16, 1
	v_lshrrev_b32_e32 v2, 16, v2
	v_add3_u32 v3, v88, v3, s65
	s_mul_i32 s2, s2, 0x1600000
	v_and_or_b32 v2, v3, s66, v2
	s_waitcnt lgkmcnt(1)
	v_bfe_u32 v3, v90, 16, 1
	s_add_u32 s2, s42, s2
	v_add3_u32 v3, v90, v3, s65
	s_waitcnt lgkmcnt(0)
	v_bfe_u32 v4, v112, 16, 1
	s_addc_u32 s3, s43, 0
	s_lshl_b32 s1, s1, 1
	v_lshrrev_b32_e32 v3, 16, v3
	v_add3_u32 v4, v112, v4, s65
	s_add_u32 s2, s2, s1
	v_and_or_b32 v3, v4, s66, v3
	v_or_b32_e32 v4, s0, v25
	s_addc_u32 s3, s3, 0
	v_lshlrev_b32_e32 v18, 1, v24
	v_mul_u32_u24_e32 v4, 0x1600, v4
	v_lshl_add_u64 v[6:7], s[2:3], 0, v[18:19]
	v_lshlrev_b32_e32 v18, 1, v4
	v_lshl_add_u64 v[114:115], v[6:7], 0, v[18:19]
	global_store_dwordx4 v[114:115], v[0:3], off nt
	v_bfe_u32 v4, v113, 16, 1
	v_add3_u32 v4, v113, v4, s65
	v_bfe_u32 v0, v5, 16, 1
	v_add3_u32 v0, v5, v0, s65
	v_bfe_u32 v1, v9, 16, 1
	v_lshrrev_b32_e32 v0, 16, v0
	v_add3_u32 v1, v9, v1, s65
	v_and_or_b32 v0, v1, s66, v0
	v_bfe_u32 v1, v11, 16, 1
	v_add3_u32 v1, v11, v1, s65
	v_bfe_u32 v2, v13, 16, 1
	v_lshrrev_b32_e32 v1, 16, v1
	v_add3_u32 v2, v13, v2, s65
	v_and_or_b32 v1, v2, s66, v1
	v_bfe_u32 v2, v15, 16, 1
	v_add3_u32 v2, v15, v2, s65
	v_bfe_u32 v3, v89, 16, 1
	v_lshrrev_b32_e32 v2, 16, v2
	v_add3_u32 v3, v89, v3, s65
	v_and_or_b32 v2, v3, s66, v2
	v_bfe_u32 v3, v91, 16, 1
	v_add3_u32 v3, v91, v3, s65
	v_lshrrev_b32_e32 v3, 16, v3
	v_and_or_b32 v3, v4, s66, v3
	v_or_b32_e32 v4, s0, v33
	v_mul_u32_u24_e32 v8, 0x1600, v4
	v_lshlrev_b32_e32 v18, 1, v8
	ds_read2_b32 v[4:5], v94 offset0:16 offset1:24
	v_lshl_add_u64 v[8:9], v[6:7], 0, v[18:19]
	global_store_dwordx4 v[8:9], v[0:3], off nt
	ds_read2_b32 v[8:9], v94 offset0:49 offset1:57
	ds_read2_b32 v[10:11], v94 offset0:82 offset1:90
	ds_read2_b32 v[12:13], v94 offset0:115 offset1:123
	s_waitcnt lgkmcnt(3)
	v_bfe_u32 v0, v4, 16, 1
	v_add3_u32 v0, v4, v0, s65
	s_waitcnt lgkmcnt(2)
	v_bfe_u32 v1, v8, 16, 1
	ds_read2_b32 v[14:15], v94 offset0:148 offset1:156
	v_lshrrev_b32_e32 v0, 16, v0
	v_add3_u32 v1, v8, v1, s65
	ds_read2_b32 v[88:89], v94 offset0:181 offset1:189
	v_and_or_b32 v0, v1, s66, v0
	s_waitcnt lgkmcnt(3)
	v_bfe_u32 v1, v10, 16, 1
	v_add3_u32 v1, v10, v1, s65
	s_waitcnt lgkmcnt(2)
	v_bfe_u32 v2, v12, 16, 1
	ds_read2_b32 v[90:91], v94 offset0:214 offset1:222
	v_lshrrev_b32_e32 v1, 16, v1
	v_add3_u32 v2, v12, v2, s65
	ds_read2_b32 v[112:113], v94 offset0:247 offset1:255
	v_and_or_b32 v1, v2, s66, v1
	s_waitcnt lgkmcnt(3)
	v_bfe_u32 v2, v14, 16, 1
	v_add3_u32 v2, v14, v2, s65
	s_waitcnt lgkmcnt(2)
	v_bfe_u32 v3, v88, 16, 1
	v_lshrrev_b32_e32 v2, 16, v2
	v_add3_u32 v3, v88, v3, s65
	v_and_or_b32 v2, v3, s66, v2
	s_waitcnt lgkmcnt(1)
	v_bfe_u32 v3, v90, 16, 1
	v_add3_u32 v3, v90, v3, s65
	s_waitcnt lgkmcnt(0)
	v_bfe_u32 v4, v112, 16, 1
	v_lshrrev_b32_e32 v3, 16, v3
	v_add3_u32 v4, v112, v4, s65
	v_and_or_b32 v3, v4, s66, v3
	v_or_b32_e32 v4, s0, v55
	v_mul_u32_u24_e32 v4, 0x1600, v4
	v_lshlrev_b32_e32 v18, 1, v4
	v_lshl_add_u64 v[114:115], v[6:7], 0, v[18:19]
	global_store_dwordx4 v[114:115], v[0:3], off nt
	v_bfe_u32 v4, v113, 16, 1
	v_add3_u32 v4, v113, v4, s65
	v_bfe_u32 v0, v5, 16, 1
	v_add3_u32 v0, v5, v0, s65
	v_bfe_u32 v1, v9, 16, 1
	v_lshrrev_b32_e32 v0, 16, v0
	v_add3_u32 v1, v9, v1, s65
	v_and_or_b32 v0, v1, s66, v0
	v_bfe_u32 v1, v11, 16, 1
	v_add3_u32 v1, v11, v1, s65
	v_bfe_u32 v2, v13, 16, 1
	v_lshrrev_b32_e32 v1, 16, v1
	v_add3_u32 v2, v13, v2, s65
	v_and_or_b32 v1, v2, s66, v1
	v_bfe_u32 v2, v15, 16, 1
	v_add3_u32 v2, v15, v2, s65
	v_bfe_u32 v3, v89, 16, 1
	v_lshrrev_b32_e32 v2, 16, v2
	v_add3_u32 v3, v89, v3, s65
	v_and_or_b32 v2, v3, s66, v2
	v_bfe_u32 v3, v91, 16, 1
	v_add3_u32 v3, v91, v3, s65
	v_lshrrev_b32_e32 v3, 16, v3
	v_and_or_b32 v3, v4, s66, v3
	v_or_b32_e32 v4, s0, v57
	v_mul_u32_u24_e32 v4, 0x1600, v4
	v_lshlrev_b32_e32 v18, 1, v4
	v_lshl_add_u64 v[4:5], v[6:7], 0, v[18:19]
	global_store_dwordx4 v[4:5], v[0:3], off nt
	s_waitcnt lgkmcnt(0)

.LBB0_111:
	s_lshl_b32 s24, s1, 1
	s_lshl_b32 s7, s5, 1
	v_or_b32_e32 v75, s24, v54
	s_add_i32 s27, s24, 4
	v_or_b32_e32 v73, s7, v17
	s_add_i32 s26, s7, 4
	s_add_i32 s71, s7, 8
	s_add_i32 s72, s24, 8
	s_add_i32 s73, s7, 12
	s_add_i32 s75, s7, 16
	s_add_i32 s77, s7, 20
	s_add_i32 s79, s7, 24
	s_add_i32 s7, s7, 28
	v_add_u32_e32 v4, s3, v75
	v_or_b32_e32 v79, s27, v54
	s_add_i32 s74, s24, 12
	v_add_u32_e32 v2, s4, v73
	v_or_b32_e32 v77, s26, v17
	v_or_b32_e32 v111, s71, v17
	v_or_b32_e32 v114, s72, v54
	v_or_b32_e32 v115, s73, v17
	v_or_b32_e32 v117, s75, v17
	v_or_b32_e32 v119, s77, v17
	v_or_b32_e32 v121, s79, v17
	v_or_b32_e32 v124, s7, v17
	v_mul_lo_u32 v18, v4, s68
	v_add_u32_e32 v6, s3, v79
	v_mov_b32_e32 v3, v19
	s_add_i32 s76, s24, 16
	v_or_b32_e32 v116, s74, v54
	v_mul_lo_u32 v2, v2, s68
	v_add_u32_e32 v4, s4, v77
	v_add_u32_e32 v125, s3, v114
	v_add_u32_e32 v8, s4, v111
	v_add_u32_e32 v10, s4, v115
	v_add_u32_e32 v12, s4, v117
	v_add_u32_e32 v14, s4, v119
	v_add_u32_e32 v88, s4, v121
	v_add_u32_e32 v112, s4, v124
	v_lshl_add_u64 v[90:91], v[18:19], 2, v[0:1]
	v_mul_lo_u32 v18, v6, s68
	v_mov_b32_e32 v5, v19
	s_add_i32 s78, s24, 20
	v_or_b32_e32 v118, s76, v54
	v_add_u32_e32 v126, s3, v116
	v_lshl_add_u64 v[2:3], v[2:3], 2, v[0:1]
	v_mul_lo_u32 v4, v4, s68
	v_mul_lo_u32 v6, v8, s68
	v_mul_lo_u32 v8, v10, s68
	v_mul_lo_u32 v10, v12, s68
	v_mul_lo_u32 v12, v14, s68
	v_mul_lo_u32 v14, v88, s68
	v_mul_lo_u32 v88, v112, s68
	v_lshl_add_u64 v[112:113], v[18:19], 2, v[0:1]
	v_mul_lo_u32 v18, v125, s68
	s_add_i32 s80, s24, 24
	v_or_b32_e32 v120, s78, v54
	v_add_u32_e32 v127, s3, v118
	v_lshl_add_u64 v[4:5], v[4:5], 2, v[0:1]
	global_load_dword v131, v[90:91], off nt
	global_load_dword v132, v[2:3], off nt
	global_load_dword v133, v[112:113], off nt
	global_load_dword v134, v[4:5], off nt
	v_lshl_add_u64 v[2:3], v[18:19], 2, v[0:1]
	v_mul_lo_u32 v18, v126, s68
	v_mov_b32_e32 v7, v19
	v_mov_b32_e32 v9, v19
	s_add_i32 s24, s24, 28
	v_or_b32_e32 v122, s80, v54
	v_add_u32_e32 v128, s3, v120
	v_lshl_add_u64 v[4:5], v[18:19], 2, v[0:1]
	v_mul_lo_u32 v18, v127, s68
	v_or_b32_e32 v123, s24, v54
	v_add_u32_e32 v129, s3, v122
	v_lshl_add_u64 v[6:7], v[6:7], 2, v[0:1]
	v_lshl_add_u64 v[8:9], v[8:9], 2, v[0:1]
	global_load_dword v126, v[2:3], off nt
	global_load_dword v127, v[6:7], off nt
	global_load_dword v135, v[4:5], off nt
	global_load_dword v136, v[8:9], off nt
	v_lshl_add_u64 v[2:3], v[18:19], 2, v[0:1]
	v_mul_lo_u32 v18, v128, s68
	v_mov_b32_e32 v11, v19
	v_mov_b32_e32 v13, v19
	v_add_u32_e32 v130, s3, v123
	v_lshl_add_u64 v[4:5], v[18:19], 2, v[0:1]
	v_mul_lo_u32 v18, v129, s68
	v_mov_b32_e32 v15, v19
	v_mov_b32_e32 v89, v19
	v_lshl_add_u64 v[10:11], v[10:11], 2, v[0:1]
	v_lshl_add_u64 v[12:13], v[12:13], 2, v[0:1]
	global_load_dword v128, v[2:3], off nt
	global_load_dword v129, v[10:11], off nt
	global_load_dword v137, v[4:5], off nt
	global_load_dword v138, v[12:13], off nt
	v_lshl_add_u64 v[2:3], v[18:19], 2, v[0:1]
	v_mul_lo_u32 v18, v130, s68
	v_lshl_add_u64 v[14:15], v[14:15], 2, v[0:1]
	v_lshl_add_u64 v[88:89], v[88:89], 2, v[0:1]
	v_lshl_add_u64 v[4:5], v[18:19], 2, v[0:1]
	global_load_dword v18, v[2:3], off nt
	global_load_dword v130, v[14:15], off nt
	global_load_dword v139, v[4:5], off nt
	global_load_dword v140, v[88:89], off nt
	s_add_i32 s1, s1, 16
	s_add_i32 s5, s5, 16
	s_add_i32 s6, s6, -16
	v_mad_u64_u32 v[2:3], s[26:27], v75, s49, v[56:57]
	s_cmp_lg_u32 s6, 0
	v_mad_u64_u32 v[4:5], s[26:27], v73, s49, v[56:57]
	v_mad_u64_u32 v[6:7], s[26:27], v79, s49, v[56:57]
	v_mad_u64_u32 v[8:9], s[26:27], v77, s49, v[56:57]
	v_mad_u64_u32 v[10:11], s[26:27], v114, s49, v[56:57]
	v_mad_u64_u32 v[12:13], s[26:27], v111, s49, v[56:57]
	v_mad_u64_u32 v[14:15], s[26:27], v116, s49, v[56:57]
	v_mad_u64_u32 v[88:89], s[26:27], v115, s49, v[56:57]
	v_mad_u64_u32 v[90:91], s[26:27], v118, s49, v[56:57]
	v_mad_u64_u32 v[112:113], s[26:27], v117, s49, v[56:57]
	v_mad_u64_u32 v[114:115], s[26:27], v120, s49, v[56:57]
	v_mad_u64_u32 v[116:117], s[26:27], v119, s49, v[56:57]
	v_mad_u64_u32 v[118:119], s[26:27], v122, s49, v[56:57]
	v_mad_u64_u32 v[120:121], s[26:27], v121, s49, v[56:57]
	v_mad_u64_u32 v[122:123], s[26:27], v123, s49, v[56:57]
	v_mad_u64_u32 v[124:125], s[26:27], v124, s49, v[56:57]
	s_waitcnt vmcnt(0)
	ds_write_b32 v2, v131
	ds_write_b32 v4, v132
	ds_write_b32 v6, v133
	ds_write_b32 v8, v134
	ds_write_b32 v10, v126
	ds_write_b32 v12, v127
	ds_write_b32 v14, v135
	ds_write_b32 v88, v136
	ds_write_b32 v90, v128
	ds_write_b32 v112, v129
	ds_write_b32 v114, v137
	ds_write_b32 v116, v138
	ds_write_b32 v118, v18
	ds_write_b32 v120, v130
	ds_write_b32 v122, v139
	ds_write_b32 v124, v140
	s_cbranch_scc1 .LBB0_111
	s_waitcnt lgkmcnt(0)
	ds_read2_b32 v[4:5], v94 offset1:8
	ds_read2_b32 v[8:9], v94 offset0:33 offset1:41
	ds_read2_b32 v[10:11], v94 offset0:66 offset1:74
	ds_read2_b32 v[12:13], v94 offset0:99 offset1:107
	ds_read2_b32 v[14:15], v94 offset0:132 offset1:140
	s_waitcnt lgkmcnt(0)
	v_bfe_u32 v0, v4, 16, 1
	v_add3_u32 v0, v4, v0, s65
	v_bfe_u32 v1, v8, 16, 1
	v_lshrrev_b32_e32 v0, 16, v0
	v_add3_u32 v1, v8, v1, s65
	ds_read2_b32 v[88:89], v94 offset0:165 offset1:173
	v_and_or_b32 v0, v1, s66, v0
	v_bfe_u32 v1, v10, 16, 1
	v_add3_u32 v1, v10, v1, s65
	v_bfe_u32 v2, v12, 16, 1
	ds_read2_b32 v[90:91], v94 offset0:198 offset1:206
	v_lshrrev_b32_e32 v1, 16, v1
	v_add3_u32 v2, v12, v2, s65
	ds_read2_b32 v[112:113], v94 offset0:231 offset1:239
	v_and_or_b32 v1, v2, s66, v1
	v_bfe_u32 v2, v14, 16, 1
	v_add3_u32 v2, v14, v2, s65
	s_waitcnt lgkmcnt(2)
	v_bfe_u32 v3, v88, 16, 1
	s_add_u32 s1, s44, s2
	v_lshrrev_b32_e32 v2, 16, v2
	v_add3_u32 v3, v88, v3, s65
	s_addc_u32 s4, s45, 0
	s_and_b32 s2, 0xffff, s3
	v_and_or_b32 v2, v3, s66, v2
	s_waitcnt lgkmcnt(1)
	v_bfe_u32 v3, v90, 16, 1
	s_lshl_b32 s2, s2, 1
	v_add3_u32 v3, v90, v3, s65
	s_waitcnt lgkmcnt(0)
	v_bfe_u32 v4, v112, 16, 1
	s_add_u32 s2, s1, s2
	v_lshrrev_b32_e32 v3, 16, v3
	v_add3_u32 v4, v112, v4, s65
	s_addc_u32 s3, s4, 0
	v_lshlrev_b32_e32 v18, 1, v24
	v_and_or_b32 v3, v4, s66, v3
	v_or_b32_e32 v4, s0, v25
	v_lshl_add_u64 v[6:7], s[2:3], 0, v[18:19]
	v_lshlrev_b32_e32 v18, 12, v4
	v_lshl_add_u64 v[114:115], v[6:7], 0, v[18:19]
	global_store_dwordx4 v[114:115], v[0:3], off nt
	v_bfe_u32 v4, v113, 16, 1
	v_or_b32_e32 v8, s0, v33
	v_bfe_u32 v0, v5, 16, 1
	v_add3_u32 v0, v5, v0, s65
	v_bfe_u32 v1, v9, 16, 1
	v_lshrrev_b32_e32 v0, 16, v0
	v_add3_u32 v1, v9, v1, s65
	v_and_or_b32 v0, v1, s66, v0
	v_bfe_u32 v1, v11, 16, 1
	v_add3_u32 v1, v11, v1, s65
	v_bfe_u32 v2, v13, 16, 1
	v_lshrrev_b32_e32 v1, 16, v1
	v_add3_u32 v2, v13, v2, s65
	v_and_or_b32 v1, v2, s66, v1
	v_bfe_u32 v2, v15, 16, 1
	v_add3_u32 v2, v15, v2, s65
	v_bfe_u32 v3, v89, 16, 1
	v_lshrrev_b32_e32 v2, 16, v2
	v_add3_u32 v3, v89, v3, s65
	v_and_or_b32 v2, v3, s66, v2
	v_bfe_u32 v3, v91, 16, 1
	v_add3_u32 v3, v91, v3, s65
	v_lshrrev_b32_e32 v3, 16, v3
	v_add3_u32 v4, v113, v4, s65
	v_lshlrev_b32_e32 v18, 12, v8
	v_and_or_b32 v3, v4, s66, v3
	ds_read2_b32 v[4:5], v94 offset0:16 offset1:24
	v_lshl_add_u64 v[8:9], v[6:7], 0, v[18:19]
	global_store_dwordx4 v[8:9], v[0:3], off nt
	ds_read2_b32 v[8:9], v94 offset0:49 offset1:57
	ds_read2_b32 v[10:11], v94 offset0:82 offset1:90
	ds_read2_b32 v[12:13], v94 offset0:115 offset1:123
	s_waitcnt lgkmcnt(3)
	v_bfe_u32 v0, v4, 16, 1
	v_add3_u32 v0, v4, v0, s65
	s_waitcnt lgkmcnt(2)
	v_bfe_u32 v1, v8, 16, 1
	ds_read2_b32 v[14:15], v94 offset0:148 offset1:156
	v_lshrrev_b32_e32 v0, 16, v0
	v_add3_u32 v1, v8, v1, s65
	ds_read2_b32 v[88:89], v94 offset0:181 offset1:189
	v_and_or_b32 v0, v1, s66, v0
	s_waitcnt lgkmcnt(3)
	v_bfe_u32 v1, v10, 16, 1
	v_add3_u32 v1, v10, v1, s65
	s_waitcnt lgkmcnt(2)
	v_bfe_u32 v2, v12, 16, 1
	ds_read2_b32 v[90:91], v94 offset0:214 offset1:222
	v_lshrrev_b32_e32 v1, 16, v1
	v_add3_u32 v2, v12, v2, s65
	ds_read2_b32 v[112:113], v94 offset0:247 offset1:255
	v_and_or_b32 v1, v2, s66, v1
	s_waitcnt lgkmcnt(3)
	v_bfe_u32 v2, v14, 16, 1
	v_add3_u32 v2, v14, v2, s65
	s_waitcnt lgkmcnt(2)
	v_bfe_u32 v3, v88, 16, 1
	v_lshrrev_b32_e32 v2, 16, v2
	v_add3_u32 v3, v88, v3, s65
	v_and_or_b32 v2, v3, s66, v2
	s_waitcnt lgkmcnt(1)
	v_bfe_u32 v3, v90, 16, 1
	v_add3_u32 v3, v90, v3, s65
	s_waitcnt lgkmcnt(0)
	v_bfe_u32 v4, v112, 16, 1
	v_lshrrev_b32_e32 v3, 16, v3
	v_add3_u32 v4, v112, v4, s65
	v_and_or_b32 v3, v4, s66, v3
	v_or_b32_e32 v4, s0, v55
	v_lshlrev_b32_e32 v18, 12, v4
	v_lshl_add_u64 v[114:115], v[6:7], 0, v[18:19]
	global_store_dwordx4 v[114:115], v[0:3], off nt
	v_bfe_u32 v4, v113, 16, 1
	v_add3_u32 v4, v113, v4, s65
	v_bfe_u32 v0, v5, 16, 1
	v_add3_u32 v0, v5, v0, s65
	v_bfe_u32 v1, v9, 16, 1
	v_lshrrev_b32_e32 v0, 16, v0
	v_add3_u32 v1, v9, v1, s65
	v_and_or_b32 v0, v1, s66, v0
	v_bfe_u32 v1, v11, 16, 1
	v_add3_u32 v1, v11, v1, s65
	v_bfe_u32 v2, v13, 16, 1
	v_lshrrev_b32_e32 v1, 16, v1
	v_add3_u32 v2, v13, v2, s65
	v_and_or_b32 v1, v2, s66, v1
	v_bfe_u32 v2, v15, 16, 1
	v_add3_u32 v2, v15, v2, s65
	v_bfe_u32 v3, v89, 16, 1
	v_lshrrev_b32_e32 v2, 16, v2
	v_add3_u32 v3, v89, v3, s65
	v_and_or_b32 v2, v3, s66, v2
	v_bfe_u32 v3, v91, 16, 1
	v_add3_u32 v3, v91, v3, s65
	v_lshrrev_b32_e32 v3, 16, v3
	v_and_or_b32 v3, v4, s66, v3
	v_or_b32_e32 v4, s0, v57
	v_lshlrev_b32_e32 v18, 12, v4
	v_lshl_add_u64 v[4:5], v[6:7], 0, v[18:19]
	global_store_dwordx4 v[4:5], v[0:3], off nt
	s_waitcnt lgkmcnt(0)
